# MLA loop: softmax scale folded into q (up-projection epilogue), -m enters QK^T as SrcC (no per-score fma), 16 more regs from rematerialised constants
# speedup vs baseline: 1.0531x; 1.0069x over previous
.LBB0_5:
	s_or_b64 exec, exec, s[0:1]
	v_readlane_b32 s0, v254, 6
	v_readlane_b32 s1, v254, 7
	s_load_dwordx4 s[4:7], s[0:1], 0x108
	s_waitcnt lgkmcnt(0)
	s_cmp_ge_i32 s4, s5
	s_cbranch_scc1 .LBB0_588
	s_lshl_b32 s0, s2, 3
	v_writelane_b32 v254, s0, 10
	s_lshl_b32 s0, s2, 9
	v_readlane_b32 s20, v254, 6
	v_readlane_b32 s21, v254, 7
	s_load_dwordx4 s[16:19], s[20:21], 0x108
	v_writelane_b32 v254, s0, 11
	v_lshrrev_b32_e32 v1, 20, v0
	v_lshrrev_b32_e32 v0, 10, v0
	v_or_b32_e32 v0, v0, v1
	s_waitcnt lgkmcnt(0)
	s_lshl_b32 s76, s18, 3
	s_lshl_b32 s78, s18, 9
	s_cmpk_lt_i32 s2, 0x400
	s_cselect_b64 s[0:1], -1, 0
	v_writelane_b32 v254, s0, 12
	s_ashr_i32 s81, s2, 31
	s_ashr_i32 s4, s18, 3
	v_writelane_b32 v254, s1, 13
	s_lshr_b32 s0, s81, 29
	s_add_i32 s1, s2, s0
	s_ashr_i32 s0, s1, 3
	s_and_b32 s1, s1, -8
	s_sub_i32 s1, s2, s1
	s_mul_i32 s4, s4, s1
	s_lshl_b32 s6, s1, 7
	s_ashr_i32 s3, s18, 31
	s_and_b32 s5, s18, 7
	s_add_i32 s4, s4, s0
	s_cmpk_lt_i32 s2, 0x300
	s_cselect_b64 s[10:11], -1, 0
	v_writelane_b32 v254, s10, 14
	s_cmpk_lt_i32 s2, 0x80
	v_mov_b32_e32 v185, 0
	v_writelane_b32 v254, s11, 15
	s_cselect_b64 s[10:11], -1, 0
	s_lshl_b32 s7, s1, 4
	v_writelane_b32 v254, s10, 16
	s_cmpk_lt_i32 s2, 0xa00
	s_mov_b32 s68, 0x6dc9c883
	v_writelane_b32 v254, s11, 17
	s_cselect_b64 s[10:11], -1, 0
	v_writelane_b32 v254, s10, 18
	s_mov_b32 s92, 0x54442d18
	v_mbcnt_lo_u32_b32 v1, -1, 0
	v_writelane_b32 v254, s11, 19
	s_load_dwordx2 s[10:11], s[20:21], 0x80
	s_movk_i32 s64, 0xe7f0
	v_mov_b32_e32 v204, 0x358637bd
	v_mov_b32_e32 v205, 0x260
	s_mov_b32 s69, 0x3fe45f30
	s_waitcnt lgkmcnt(0)
	s_add_u32 s12, s10, 0x200
	s_addc_u32 s13, s11, 0
	v_writelane_b32 v254, s12, 20
	s_mov_b32 s93, 0xbff921fb
	v_mov_b32_e32 v206, 1
	v_writelane_b32 v254, s13, 21
	s_add_u32 s12, s10, 0x1000
	s_addc_u32 s13, s11, 0
	v_writelane_b32 v254, s12, 22
	v_mov_b64_e32 v[210:211], 0x400
	v_mov_b64_e32 v[234:235], 0x3ff
	v_writelane_b32 v254, s13, 23
	s_add_u32 s12, s10, 0x1100
	s_addc_u32 s13, s11, 0
	v_writelane_b32 v254, s12, 24
	v_mov_b32_e32 v207, 0xf149f2ca
	v_mbcnt_hi_u32_b32 v208, -1, v1
	v_writelane_b32 v254, s13, 25
	s_add_u32 s12, s10, 0x1200
	s_addc_u32 s13, s11, 0
	v_writelane_b32 v254, s12, 26
	v_mov_b32_e32 v236, 0x1450
	v_mov_b32_e32 v209, 0x1c70
	v_writelane_b32 v254, s13, 27
	s_add_u32 s12, s10, 0x1300
	s_addc_u32 s13, s11, 0
	v_writelane_b32 v254, s12, 28
	s_cmp_eq_u32 s8, 15
	v_mov_b32_e32 v212, 0x2490
	v_writelane_b32 v254, s13, 29
	s_cselect_b64 s[12:13], -1, 0
	v_writelane_b32 v254, s12, 30
	s_cmp_eq_u32 s8, 14
	v_mov_b32_e32 v237, 0x28a0
	v_writelane_b32 v254, s13, 31
	s_cselect_b64 s[12:13], -1, 0
	v_writelane_b32 v254, s12, 32
	s_cmp_eq_u32 s8, 13
	v_mov_b32_e32 v242, v185
	v_writelane_b32 v254, s13, 33
	s_cselect_b64 s[12:13], -1, 0
	v_writelane_b32 v254, s12, 34
	s_cmp_eq_u32 s8, 12
	v_mov_b32_e32 v243, v185
	v_writelane_b32 v254, s13, 35
	s_cselect_b64 s[12:13], -1, 0
	v_writelane_b32 v254, s12, 36
	s_cmp_eq_u32 s8, 11
	v_mov_b32_e32 v244, v185
	v_writelane_b32 v254, s13, 37
	s_cselect_b64 s[12:13], -1, 0
	v_writelane_b32 v254, s12, 38
	s_cmp_eq_u32 s8, 10
	v_mov_b32_e32 v245, v185
	v_writelane_b32 v254, s13, 39
	s_cselect_b64 s[12:13], -1, 0
	v_writelane_b32 v254, s12, 40
	s_cmp_eq_u32 s8, 9
	s_mov_b32 s71, 0x10000
	v_writelane_b32 v254, s13, 41
	s_cselect_b64 s[12:13], -1, 0
	v_writelane_b32 v254, s12, 42
	s_cmp_eq_u32 s8, 8
	s_mov_b32 s70, 0x14000
	v_writelane_b32 v254, s13, 43
	s_cselect_b64 s[12:13], -1, 0
	v_writelane_b32 v254, s12, 44
	s_cmp_eq_u32 s8, 7
	s_mov_b32 s95, 0xffff0000
	v_writelane_b32 v254, s13, 45
	s_cselect_b64 s[12:13], -1, 0
	v_writelane_b32 v254, s12, 46
	s_cmp_eq_u32 s8, 6
	s_movk_i32 s73, 0xc00
	v_writelane_b32 v254, s13, 47
	s_cselect_b64 s[12:13], -1, 0
	v_writelane_b32 v254, s12, 48
	s_cmp_eq_u32 s8, 5
	s_mov_b32 s97, 0x4138aa3b
	v_writelane_b32 v254, s13, 49
	s_cselect_b64 s[12:13], -1, 0
	v_writelane_b32 v254, s12, 50
	s_cmp_eq_u32 s8, 4
	s_movk_i32 s90, 0x2800
	v_writelane_b32 v254, s13, 51
	s_cselect_b64 s[12:13], -1, 0
	v_writelane_b32 v254, s12, 52
	s_cmp_eq_u32 s8, 3
	s_mov_b32 s53, 0x1b400000
	v_writelane_b32 v254, s13, 53
	s_cselect_b64 s[12:13], -1, 0
	v_writelane_b32 v254, s12, 54
	s_cmp_eq_u32 s8, 2
	s_movk_i32 s91, 0x7fff
	v_writelane_b32 v254, s13, 55
	s_cselect_b64 s[12:13], -1, 0
	v_writelane_b32 v254, s12, 56
	s_cmp_eq_u32 s8, 1
	s_movk_i32 s54, 0x1000
	v_writelane_b32 v254, s13, 57
	s_cselect_b64 s[12:13], -1, 0
	v_writelane_b32 v254, s12, 58
	s_cmp_eq_u32 s8, 0
	s_mov_b32 s94, 0xf800000
	v_writelane_b32 v254, s13, 59
	s_cselect_b64 s[12:13], -1, 0
	s_lshl_b32 s8, s8, 8
	s_add_u32 s8, s10, s8
	v_writelane_b32 v254, s12, 60
	s_addc_u32 s9, s11, 0
	s_mov_b32 s17, 0
	v_writelane_b32 v254, s13, 61
	s_add_u32 s12, s8, 0x1400
	s_addc_u32 s13, s9, 0
	s_add_u32 s8, s8, 0x2400
	s_addc_u32 s9, s9, 0
	v_writelane_b32 v255, s8, 0
	v_writelane_b32 v254, s12, 62
	s_movk_i32 s67, 0x2000
	v_writelane_b32 v255, s9, 1
	s_add_u32 s8, s10, 0x3400
	s_addc_u32 s9, s11, 0
	v_writelane_b32 v255, s8, 2
	v_writelane_b32 v254, s13, 63
	s_mov_b64 s[22:23], 0x80000
	v_writelane_b32 v255, s9, 3
	s_add_u32 s8, s10, 0x3500
	s_addc_u32 s9, s11, 0
	v_writelane_b32 v255, s8, 4
	s_cmp_lt_i32 s1, 0
	s_mov_b64 s[26:27], 0x80
	v_writelane_b32 v255, s9, 5
	s_mul_i32 s8, s1, 0x81
	s_cselect_b32 s6, s8, s6
	s_mul_i32 s8, s1, 17
	s_cselect_b32 s8, s8, s7
	s_movk_i32 s7, 0x61
	s_cselect_b32 s9, s7, 0x60
	s_movk_i32 s7, 0x141
	s_cselect_b32 s10, s7, 0x140
	s_add_i32 s6, s6, s0
	s_ashr_i32 s7, s6, 31
	s_lshr_b32 s7, s7, 26
	s_add_i32 s7, s6, s7
	s_and_b32 s11, s7, 0xffc0
	s_sub_i32 s6, s6, s11
	s_bfe_i32 s11, s6, 0x80000
	s_bfe_u32 s11, s11, 0x3000c
	s_add_i32 s11, s6, s11
	s_and_b32 s12, s11, 0xf8
	s_sub_i32 s6, s6, s12
	s_ashr_i32 s7, s7, 6
	s_bfe_i32 s11, s11, 0x80000
	s_lshl_b32 s7, s7, 3
	s_sext_i32_i16 s11, s11
	s_sext_i32_i8 s6, s6
	s_add_i32 s14, s7, s6
	s_ashr_i32 s6, s11, 3
	v_writelane_b32 v255, s6, 6
	s_mov_b32 s12, s14
	s_ashr_i32 s15, s14, 31
	s_lshr_b32 s6, s11, 3
	v_writelane_b32 v255, s12, 7
	s_load_dword s11, s[20:21], 0x118
	s_bfe_i64 s[6:7], s[6:7], 0x100000
	v_writelane_b32 v255, s13, 8
	s_lshl_b64 s[12:13], s[14:15], 20
	v_writelane_b32 v255, s12, 9
	s_mov_b32 s80, 0x3dd53b94
	s_mov_b64 s[28:29], 0x13480000
	v_writelane_b32 v255, s13, 10
	s_lshl_b64 s[12:13], s[6:7], 20
	v_writelane_b32 v255, s12, 11
	s_cmp_eq_u32 s5, 0
	s_mul_i32 s5, s19, s18
	v_writelane_b32 v255, s13, 12
	s_waitcnt lgkmcnt(0)
	s_mul_i32 s5, s5, s11
	v_writelane_b32 v255, s5, 13
	s_cselect_b32 s4, s4, s2
	v_writelane_b32 v255, s4, 14
	s_cmpk_lt_i32 s4, 0x400
	s_mul_i32 s4, s1, s9
	s_movk_i32 s5, 0x3ff
	s_cselect_b64 s[12:13], -1, 0
	s_add_i32 s4, s4, s0
	v_and_or_b32 v0, v0, s5, v203
	s_mul_hi_i32 s5, s4, 0x2aaaaaab
	s_lshr_b32 s9, s5, 31
	s_ashr_i32 s5, s5, 3
	s_add_i32 s5, s5, s9
	s_mul_i32 s9, s5, 48
	s_sub_i32 s4, s4, s9
	s_bfe_i32 s9, s4, 0x80000
	s_bfe_u32 s9, s9, 0x3000c
	s_add_i32 s9, s4, s9
	s_and_b32 s11, s9, 0xf8
	s_sub_i32 s4, s4, s11
	v_writelane_b32 v255, s12, 15
	s_lshl_b32 s5, s5, 3
	s_sext_i32_i8 s4, s4
	v_writelane_b32 v255, s13, 16
	s_add_i32 s4, s5, s4
	v_writelane_b32 v255, s4, 17
	s_add_i32 s4, s8, s0
	s_ashr_i32 s5, s4, 31
	s_lshr_b32 s5, s5, 25
	s_mul_i32 s1, s1, s10
	s_add_i32 s5, s4, s5
	s_add_i32 s1, s1, s0
	s_and_b32 s8, s5, 0xff80
	s_mul_hi_i32 s0, s1, 0x66666667
	s_sub_i32 s4, s4, s8
	s_lshr_b32 s10, s0, 31
	s_ashr_i32 s0, s0, 6
	s_bfe_i32 s8, s4, 0x80000
	s_add_i32 s10, s0, s10
	s_bfe_u32 s8, s8, 0x3000c
	s_mul_i32 s0, s10, 0xa0
	s_add_i32 s8, s4, s8
	s_sub_i32 s0, s1, s0
	s_and_b32 s11, s8, 0xf8
	s_bfe_u32 s1, s0, 0x3001c
	s_sub_i32 s4, s4, s11
	s_add_i32 s11, s0, s1
	s_and_b32 s1, s11, 0xfff8
	s_sub_i32 s12, s0, s1
	s_bfe_i32 s0, s9, 0x80000
	s_sext_i32_i16 s0, s0
	s_ashr_i32 s1, s0, 3
	s_lshr_b32 s0, s0, 3
	v_writelane_b32 v255, s1, 18
	s_bfe_i64 s[0:1], s[0:1], 0x100000
	s_lshl_b64 s[0:1], s[0:1], 18
	v_writelane_b32 v255, s0, 19
	s_sext_i32_i8 s4, s4
	s_ashr_i32 s79, s78, 31
	v_writelane_b32 v255, s1, 20
	s_lshl_b64 s[0:1], s[6:7], 17
	v_writelane_b32 v255, s0, 21
	s_lshl_b32 s66, s18, 11
	s_ashr_i32 s77, s76, 31
	v_writelane_b32 v255, s1, 22
	s_ashr_i32 s0, s5, 7
	s_bfe_i32 s1, s8, 0x80000
	s_lshl_b32 s0, s0, 3
	s_sext_i32_i16 s1, s1
	s_add_i32 s6, s0, s4
	s_ashr_i32 s0, s1, 3
	v_writelane_b32 v255, s0, 23
	s_lshr_b32 s0, s1, 3
	s_bfe_i64 s[0:1], s[0:1], 0x100000
	s_lshl_b64 s[0:1], s[0:1], 20
	v_writelane_b32 v255, s0, 24
	s_sext_i32_i16 s4, s12
	s_ashr_i32 s7, s6, 31
	v_writelane_b32 v255, s1, 25
	s_lshl_b32 s0, s10, 3
	s_sext_i32_i16 s1, s11
	s_add_i32 s4, s0, s4
	s_ashr_i32 s0, s1, 3
	v_writelane_b32 v255, s0, 26
	s_lshr_b32 s0, s1, 3
	s_bfe_i64 s[0:1], s[0:1], 0x100000
	s_lshl_b64 s[0:1], s[0:1], 20
	v_writelane_b32 v255, s0, 27
	s_ashr_i32 s5, s4, 31
	s_lshl_b32 s51, s18, 12
	v_writelane_b32 v255, s1, 28
	s_lshl_b32 s0, s2, 11
	v_writelane_b32 v255, s0, 29
	s_lshl_b32 s0, s2, 12
	v_writelane_b32 v255, s0, 30
	s_add_i32 s0, 0, 0x20810
	v_writelane_b32 v255, s0, 31
	s_add_i32 s0, 0, 0x20800
	v_writelane_b32 v255, s0, 32
	s_add_i32 s0, 0, 0x20804
	v_writelane_b32 v255, s0, 33
	v_cmp_eq_u32_e64 s[0:1], 0, v0
	s_lshl_b64 s[84:85], s[76:77], 2
	s_lshl_b64 s[18:19], s[76:77], 13
	v_writelane_b32 v255, s0, 34
	s_mov_b64 s[86:87], 0x134c0000
	s_mov_b32 s65, -1
	v_writelane_b32 v255, s1, 35
	s_mov_b32 s0, s6
	v_writelane_b32 v255, s0, 36
	s_nop 1
	v_writelane_b32 v255, s1, 37
	s_lshl_b64 s[0:1], s[6:7], 20
	v_writelane_b32 v255, s0, 38
	s_nop 1
	v_writelane_b32 v255, s1, 39
	s_mov_b32 s0, s4
	v_writelane_b32 v255, s0, 40
	s_nop 1
	v_writelane_b32 v255, s1, 41
	s_lshl_b64 s[0:1], s[4:5], 20
	v_writelane_b32 v255, s0, 42
	s_lshl_b64 s[4:5], s[76:77], 12
	s_mov_b32 s77, 0x8000
	v_writelane_b32 v255, s1, 43
	s_lshl_b64 s[0:1], s[78:79], 2
	v_writelane_b32 v255, s0, 44
	s_nop 1
	v_writelane_b32 v255, s1, 45
	v_writelane_b32 v255, s66, 46
	v_writelane_b32 v255, s51, 47
	s_branch .LBB0_11

.LBB0_41:
	s_ashr_i32 s8, s46, 7
	s_ashr_i32 s9, s8, 31
	s_lshl_b32 s13, s46, 8
	s_lshl_b64 s[6:7], s[8:9], 12
	s_and_b32 s13, s13, 0xf00
	s_or_b32 s6, s6, s13
	s_bfe_u32 s36, s46, 0x30004
	s_mul_i32 s13, s7, 0xc00
	s_mul_hi_u32 s14, s6, 0xc00
	s_lshl_b32 s12, s36, 9
	s_add_i32 s14, s14, s13
	s_mul_i32 s13, s6, 0xc00
	s_add_u32 s13, s11, s13
	s_addc_u32 s14, s24, s14
	s_mul_i32 s15, s36, 0x180
	s_add_u32 s20, s13, s15
	s_addc_u32 s21, s14, 0
	s_lshl_b64 s[14:15], s[8:9], 24
	s_add_u32 s13, s25, s14
	s_addc_u32 s33, s30, s15
	s_add_u32 s44, s13, s12
	s_addc_u32 s45, s33, 0
	s_lshl_b64 s[42:43], s[8:9], 19
	s_add_u32 s40, s31, s42
	s_addc_u32 s41, s38, s43
	s_lshl_b64 s[8:9], s[6:7], 7
	s_add_u32 s48, s39, s8
	s_addc_u32 s49, s79, s9
	s_add_u32 s50, s88, s8
	v_mov_b32_e32 v62, v203
	s_addc_u32 s51, s71, s9
	v_mov_b64_e32 v[0:1], s[20:21]
	v_readfirstlane_b32 s9, v62
	s_ashr_i32 s35, s9, 6
	v_and_b32_e32 v63, 31, v62
	s_lshl_b32 s34, s35, 5
	v_or_b32_e32 v2, s34, v63
	v_lshrrev_b32_e32 v50, 1, v62
	v_mad_i64_i32 v[0:1], s[20:21], v2, s73, v[0:1]
	v_and_b32_e32 v184, 16, v50
	v_lshl_add_u64 v[26:27], v[0:1], 0, v[184:185]
	v_lshlrev_b32_e32 v0, 5, v2
	global_load_dwordx4 v[2:5], v[26:27], off offset:256
	global_load_dwordx4 v[6:9], v[26:27], off offset:320
	v_ashrrev_i32_e32 v1, 31, v0
	v_lshlrev_b64 v[10:11], 2, v[0:1]
	v_lshl_add_u64 v[12:13], s[48:49], 0, v[10:11]
	v_and_b32_e32 v0, 32, v62
	v_mov_b32_e32 v1, v185
	v_lshl_add_u64 v[10:11], s[50:51], 0, v[10:11]
	v_lshl_add_u64 v[28:29], v[10:11], 0, v[0:1]
	v_lshl_add_u64 v[30:31], v[12:13], 0, v[0:1]
	global_load_dwordx4 v[10:13], v[28:29], off
	global_load_dwordx4 v[14:17], v[30:31], off
	global_load_dwordx4 v[18:21], v[28:29], off offset:16
	global_load_dwordx4 v[22:25], v[30:31], off offset:16
	global_load_dwordx4 v[124:127], v[26:27], off
	global_load_dwordx4 v[120:123], v[26:27], off offset:32
	global_load_dwordx4 v[116:119], v[26:27], off offset:64
	global_load_dwordx4 v[112:115], v[26:27], off offset:96
	global_load_dwordx4 v[108:111], v[26:27], off offset:128
	global_load_dwordx4 v[104:107], v[26:27], off offset:160
	global_load_dwordx4 v[100:103], v[26:27], off offset:192
	global_load_dwordx4 v[96:99], v[26:27], off offset:224
	s_and_b32 s8, s9, 0x3fffffc0
	s_lshl_b32 s8, s8, 2
	s_lshl_b32 s9, s35, 12
	v_and_b32_e32 v160, 63, v62
	s_add_i32 s37, s8, 0
	s_add_i32 s8, s9, 0
	v_lshlrev_b32_e32 v64, 4, v160
	s_add_i32 s8, s8, 0x18800
	v_add_u32_e32 v164, s8, v64
	s_lshl_b32 s20, s35, 3
	s_lshl_b32 s8, s35, 2
	s_and_b32 s8, s8, 4
	s_add_i32 s37, s37, 0x18000
	v_mov_b32_e32 v59, v185
	s_cmp_lg_u32 0, -1
	s_cselect_b32 s13, 0, 0
	v_or_b32_e32 v68, 0x60, v184
	v_lshlrev_b32_e32 v69, 7, v63
	s_mov_b32 s52, 0
	s_mov_b32 s53, s52
	s_mov_b32 s54, s52
	s_mov_b32 s55, s52
	s_mov_b32 s56, s52
	s_mov_b32 s57, s52
	s_mov_b32 s58, s52
	s_mov_b32 s59, s52
	s_mov_b32 s60, s52
	s_mov_b32 s61, s52
	s_mov_b32 s62, s52
	s_mov_b32 s63, s52
	s_mov_b32 s64, s52
	s_mov_b32 s65, s52
	s_mov_b32 s66, s52
	s_mov_b32 s67, s52
	v_lshl_add_u32 v162, v63, 2, s37
	s_mov_b32 s49, 2
	s_mov_b32 s48, -1
	v_mov_b32_e32 v163, 0
	s_waitcnt vmcnt(0)
	v_mov_b32_e32 v42, v12
	v_lshlrev_b32_e32 v33, 16, v2
	v_and_b32_e32 v35, 0xffff0000, v2
	v_lshlrev_b32_e32 v37, 16, v3
	v_and_b32_e32 v3, 0xffff0000, v3
	v_and_b32_e32 v2, 0xffff0000, v7
	v_mov_b32_e32 v43, v16
	v_mov_b32_e32 v44, v16
	v_mov_b32_e32 v45, v12
	v_mov_b32_e32 v16, v13
	v_mov_b32_e32 v12, v17
	v_lshlrev_b32_e32 v32, 16, v6
	v_and_b32_e32 v34, 0xffff0000, v6
	v_lshlrev_b32_e32 v36, 16, v7
	v_lshlrev_b32_e32 v7, 16, v4
	v_lshlrev_b32_e32 v6, 16, v8
	v_mov_b32_e32 v46, v18
	v_mov_b32_e32 v47, v22
	v_mov_b32_e32 v48, v22
	v_mov_b32_e32 v49, v18
	v_pk_mul_f32 v[16:17], v[16:17], v[2:3]
	v_pk_mul_f32 v[2:3], v[12:13], v[2:3]
	v_pk_mul_f32 v[12:13], v[46:47], v[6:7]
	v_sub_f32_e32 v16, v17, v16
	v_add_f32_e32 v17, v2, v3
	v_pk_mul_f32 v[2:3], v[48:49], v[6:7]
	v_sub_f32_e32 v12, v13, v12
	v_add_f32_e32 v13, v2, v3
	v_and_b32_e32 v3, 0xffff0000, v4
	v_and_b32_e32 v2, 0xffff0000, v8
	v_mov_b32_e32 v22, v19
	v_mov_b32_e32 v18, v23
	v_pk_mul_f32 v[6:7], v[22:23], v[2:3]
	v_pk_mul_f32 v[2:3], v[18:19], v[2:3]
	v_sub_f32_e32 v8, v7, v6
	v_add_f32_e32 v18, v2, v3
	v_lshlrev_b32_e32 v3, 16, v5
	v_lshlrev_b32_e32 v2, 16, v9
	v_mov_b32_e32 v6, v20
	v_mov_b32_e32 v7, v24
	v_pk_mul_f32 v[6:7], v[6:7], v[2:3]
	v_mov_b32_e32 v38, v10
	v_sub_f32_e32 v19, v7, v6
	v_mov_b32_e32 v6, v24
	v_mov_b32_e32 v7, v20
	v_pk_mul_f32 v[2:3], v[6:7], v[2:3]
	v_mov_b32_e32 v39, v14
	v_mov_b32_e32 v40, v14
	v_mov_b32_e32 v41, v10
	v_mov_b32_e32 v14, v11
	v_mov_b32_e32 v10, v15
	v_add_f32_e32 v22, v2, v3
	v_and_b32_e32 v3, 0xffff0000, v5
	v_and_b32_e32 v2, 0xffff0000, v9
	v_mov_b32_e32 v24, v21
	v_mov_b32_e32 v20, v25
	v_pk_mul_f32 v[38:39], v[38:39], v[32:33]
	v_pk_mul_f32 v[32:33], v[40:41], v[32:33]
	v_pk_mul_f32 v[14:15], v[14:15], v[34:35]
	v_pk_mul_f32 v[10:11], v[10:11], v[34:35]
	v_pk_mul_f32 v[34:35], v[42:43], v[36:37]
	v_pk_mul_f32 v[36:37], v[44:45], v[36:37]
	v_pk_mul_f32 v[4:5], v[24:25], v[2:3]
	v_pk_mul_f32 v[2:3], v[20:21], v[2:3]
	v_add_f32_e32 v32, v32, v33
	v_sub_f32_e32 v14, v15, v14
	v_add_f32_e32 v10, v10, v11
	v_sub_f32_e32 v11, v35, v34
	v_add_f32_e32 v15, v36, v37
	v_sub_f32_e32 v5, v5, v4
	v_add_f32_e32 v9, v2, v3
	v_sub_f32_e32 v1, v39, v38
	v_cvt_pk_bf16_f32 v2, v1, v14
	v_cvt_pk_bf16_f32 v3, v11, v16
	v_cvt_pk_bf16_f32 v4, v12, v8
	v_cvt_pk_bf16_f32 v5, v19, v5
	v_cvt_pk_bf16_f32 v6, v32, v10
	v_cvt_pk_bf16_f32 v7, v15, v17
	v_cvt_pk_bf16_f32 v8, v13, v18
	v_cvt_pk_bf16_f32 v9, v22, v9
	global_load_dwordx4 v[10:13], v[26:27], off offset:288
	global_load_dwordx4 v[14:17], v[26:27], off offset:352
	global_load_dwordx4 v[18:21], v[28:29], off offset:64
	global_load_dwordx4 v[22:25], v[30:31], off offset:64
	s_nop 0
	global_load_dwordx4 v[26:29], v[28:29], off offset:80
	s_nop 0
	global_load_dwordx4 v[30:33], v[30:31], off offset:80
	ds_write_b128 v164, v[2:5]
	ds_write_b128 v164, v[6:9] offset:2048
	s_waitcnt vmcnt(5)
	v_lshlrev_b32_e32 v3, 16, v10
	s_waitcnt vmcnt(4)
	v_lshlrev_b32_e32 v2, 16, v14
	s_waitcnt vmcnt(3)
	v_mov_b32_e32 v4, v18
	s_waitcnt vmcnt(2)
	v_mov_b32_e32 v5, v22
	v_mov_b32_e32 v6, v22
	v_mov_b32_e32 v7, v18
	v_and_b32_e32 v9, 0xffff0000, v10
	v_lshlrev_b32_e32 v35, 16, v11
	v_mov_b32_e32 v37, v24
	v_mov_b32_e32 v38, v24
	v_and_b32_e32 v11, 0xffff0000, v11
	v_pk_mul_f32 v[4:5], v[4:5], v[2:3]
	v_pk_mul_f32 v[2:3], v[6:7], v[2:3]
	v_and_b32_e32 v10, 0xffff0000, v15
	v_mov_b32_e32 v24, v21
	v_and_b32_e32 v8, 0xffff0000, v14
	v_mov_b32_e32 v36, v20
	v_mov_b32_e32 v39, v20
	v_add_f32_e32 v14, v2, v3
	v_pk_mul_f32 v[2:3], v[24:25], v[10:11]
	v_mov_b32_e32 v20, v25
	v_lshlrev_b32_e32 v34, 16, v15
	v_sub_f32_e32 v15, v3, v2
	v_pk_mul_f32 v[2:3], v[20:21], v[10:11]
	v_sub_f32_e32 v1, v5, v4
	v_add_f32_e32 v10, v2, v3
	v_lshlrev_b32_e32 v3, 16, v12
	v_lshlrev_b32_e32 v2, 16, v16
	s_waitcnt vmcnt(1)
	v_mov_b32_e32 v4, v26
	s_waitcnt vmcnt(0)
	v_mov_b32_e32 v5, v30
	v_pk_mul_f32 v[4:5], v[4:5], v[2:3]
	v_mov_b32_e32 v22, v19
	v_mov_b32_e32 v18, v23
	v_sub_f32_e32 v11, v5, v4
	v_mov_b32_e32 v4, v30
	v_mov_b32_e32 v5, v26
	v_pk_mul_f32 v[6:7], v[22:23], v[8:9]
	v_pk_mul_f32 v[8:9], v[18:19], v[8:9]
	v_pk_mul_f32 v[18:19], v[36:37], v[34:35]
	v_pk_mul_f32 v[2:3], v[4:5], v[2:3]
	v_sub_f32_e32 v6, v7, v6
	v_add_f32_e32 v7, v8, v9
	v_sub_f32_e32 v8, v19, v18
	v_add_f32_e32 v18, v2, v3
	v_and_b32_e32 v3, 0xffff0000, v12
	v_and_b32_e32 v2, 0xffff0000, v16
	v_mov_b32_e32 v30, v27
	v_mov_b32_e32 v26, v31
	v_pk_mul_f32 v[4:5], v[30:31], v[2:3]
	v_pk_mul_f32 v[2:3], v[26:27], v[2:3]
	v_sub_f32_e32 v12, v5, v4
	v_add_f32_e32 v16, v2, v3
	v_lshlrev_b32_e32 v3, 16, v13
	v_lshlrev_b32_e32 v2, 16, v17
	v_mov_b32_e32 v4, v28
	v_mov_b32_e32 v5, v32
	v_pk_mul_f32 v[4:5], v[4:5], v[2:3]
	v_pk_mul_f32 v[22:23], v[38:39], v[34:35]
	v_sub_f32_e32 v19, v5, v4
	v_mov_b32_e32 v4, v32
	v_mov_b32_e32 v5, v28
	v_pk_mul_f32 v[2:3], v[4:5], v[2:3]
	v_mov_b32_e32 v32, v29
	v_add_f32_e32 v20, v2, v3
	v_and_b32_e32 v3, 0xffff0000, v13
	v_and_b32_e32 v2, 0xffff0000, v17
	v_pk_mul_f32 v[4:5], v[32:33], v[2:3]
	v_mov_b32_e32 v28, v33
	v_sub_f32_e32 v5, v5, v4
	v_pk_mul_f32 v[2:3], v[28:29], v[2:3]
	v_add_f32_e32 v9, v22, v23
	v_add_f32_e32 v13, v2, v3
	v_cvt_pk_bf16_f32 v2, v1, v6
	v_cvt_pk_bf16_f32 v3, v8, v15
	v_cvt_pk_bf16_f32 v4, v11, v12
	v_cvt_pk_bf16_f32 v5, v19, v5
	v_cvt_pk_bf16_f32 v6, v14, v7
	v_cvt_pk_bf16_f32 v7, v9, v10
	v_cvt_pk_bf16_f32 v8, v18, v16
	v_cvt_pk_bf16_f32 v9, v20, v13
	ds_write_b128 v164, v[2:5] offset:1024
	ds_write_b128 v164, v[6:9] offset:3072
	v_bfe_u32 v2, v62, 2, 3
	v_bitop3_b32 v2, s20, -13, v2 bitop3:0xc8
	v_and_b32_e32 v3, 8, v50
	v_bfe_u32 v1, v62, 4, 2
	v_or3_b32 v2, v2, v3, s8
	v_lshlrev_b32_e32 v14, 3, v62
	v_ashrrev_i32_e32 v3, 31, v2
	v_or_b32_e32 v48, s20, v1
	v_lshlrev_b64 v[50:51], 12, v[2:3]
	v_bitop3_b32 v1, s20, v62, v1 bitop3:0x36
	v_ashrrev_i32_e32 v49, 31, v48
	v_and_or_b32 v0, v14, 24, v0
	v_or_b32_e32 v54, 4, v48
	v_lshl_add_u64 v[2:3], s[44:45], 0, v[50:51]
	v_lshlrev_b64 v[52:53], 12, v[48:49]
	v_lshlrev_b32_e32 v1, 4, v1
	v_lshlrev_b32_e32 v58, 1, v0
	v_bitop3_b32 v8, v48, v62, 4 bitop3:0x36
	v_ashrrev_i32_e32 v55, 31, v54
	v_lshl_add_u64 v[4:5], s[44:45], 0, v[52:53]
	v_and_b32_e32 v6, 0xf0, v1
	v_mov_b32_e32 v7, v185
	v_lshl_add_u64 v[0:1], v[2:3], 0, v[58:59]
	s_mov_b64 s[8:9], 0x100
	v_lshlrev_b64 v[56:57], 12, v[54:55]
	v_lshlrev_b32_e32 v8, 4, v8
	v_lshl_add_u64 v[4:5], v[4:5], 0, v[6:7]
	v_lshl_add_u64 v[2:3], v[0:1], 0, s[8:9]
	v_lshl_add_u64 v[6:7], s[44:45], 0, v[56:57]
	v_and_b32_e32 v8, 0xf0, v8
	v_mov_b32_e32 v9, v185
	s_mov_b64 s[8:9], 0x180
	s_lshl_b32 s44, s35, 11
	v_lshl_add_u64 v[6:7], v[6:7], 0, v[8:9]
	v_lshl_add_u64 v[8:9], v[0:1], 0, s[8:9]
	v_bfe_u32 v10, v62, 3, 3
	s_add_i32 s8, s13, s44
	v_or_b32_e32 v10, s20, v10
	s_add_i32 s45, s8, 0xc000
	v_lshrrev_b32_e32 v49, 1, v10
	s_mov_b32 m0, s45
	s_add_i32 s77, s8, 0xc400
	v_xor_b32_e32 v12, v49, v62
	v_ashrrev_i32_e32 v11, 31, v10
	global_load_lds_dwordx4 v[4:5], off
	s_mov_b32 m0, s77
	s_lshl_b32 s9, s35, 10
	v_lshlrev_b64 v[60:61], 7, v[10:11]
	v_lshlrev_b32_e32 v12, 4, v12
	s_or_b32 s47, s44, 0x400
	global_load_lds_dwordx4 v[6:7], off
	s_mov_b32 m0, s8
	s_add_i32 s33, s13, s9
	v_lshl_add_u64 v[10:11], s[40:41], 0, v[60:61]
	v_and_b32_e32 v12, 0x70, v12
	v_mov_b32_e32 v13, v185
	global_load_lds_dwordx4 v[2:3], off
	s_add_i32 m0, s47, s13
	s_add_i32 s9, s33, 0x14000
	v_lshl_add_u64 v[10:11], v[10:11], 0, v[12:13]
	global_load_lds_dwordx4 v[8:9], off
	s_mov_b32 m0, s9
	s_mov_b64 s[20:21], 0x40000
	s_add_i32 s93, s8, 0x10000
	global_load_lds_dwordx4 v[10:11], off
	v_lshl_add_u64 v[2:3], v[4:5], 0, s[20:21]
	s_mov_b32 m0, s93
	s_add_i32 s50, s8, 0x10400
	global_load_lds_dwordx4 v[2:3], off
	v_lshl_add_u64 v[2:3], v[6:7], 0, s[20:21]
	s_mov_b32 m0, s50
	s_mov_b64 s[20:21], 0x40100
	global_load_lds_dwordx4 v[2:3], off
	v_lshl_add_u64 v[2:3], v[0:1], 0, s[20:21]
	s_add_i32 m0, s8, 0x4000
	s_mov_b64 s[20:21], 0x40180
	global_load_lds_dwordx4 v[2:3], off
	v_lshl_add_u64 v[0:1], v[0:1], 0, s[20:21]
	s_add_i32 m0, s8, 0x4400
	s_mov_b64 s[20:21], 0x2000
	s_add_i32 s51, s33, 0x16000
	global_load_lds_dwordx4 v[0:1], off
	v_lshl_add_u64 v[0:1], v[10:11], 0, s[20:21]
	s_mov_b32 m0, s51
	v_lshlrev_b32_e32 v8, 8, v63
	global_load_lds_dwordx4 v[0:1], off
	v_lshlrev_b32_e32 v0, 4, v62
	v_and_b32_e32 v9, 0xf0, v0
	v_bitop3_b32 v166, v184, v8, v9 bitop3:0xde
	s_waitcnt vmcnt(0) lgkmcnt(0)
	s_barrier
	v_add_u32_e32 v167, 0, v166
	ds_read_b128 v[0:3], v167 offset:49152
	ds_read_b128 v[4:7], v167 offset:57344
	s_waitcnt lgkmcnt(0)
	v_mfma_f32_32x32x16_bf16 v[32:47], v[0:3], v[124:127], 0
	v_or_b32_e32 v55, 32, v184
	v_bitop3_b32 v168, v55, v8, v9 bitop3:0xde
	v_add_u32_e32 v169, 0, v168
	v_or_b32_e32 v59, 64, v184
	v_bitop3_b32 v170, v59, v8, v9 bitop3:0xde
	v_add_u32_e32 v171, 0, v170
	v_bitop3_b32 v172, v68, v8, v9 bitop3:0xde
	v_mfma_f32_32x32x16_bf16 v[16:31], v[4:7], v[124:127], 0
	ds_read_b128 v[0:3], v169 offset:49152
	ds_read_b128 v[4:7], v169 offset:57344
	v_add_u32_e32 v173, 0, v172
	v_and_b32_e32 v70, 0x70, v14
	v_bitop3_b32 v182, v184, v69, v70 bitop3:0xde
	s_add_i32 s8, 0, 0x14000
	v_add_u32_e32 v183, s8, v182
	v_bitop3_b32 v192, v55, v69, v70 bitop3:0xde
	s_waitcnt lgkmcnt(0)
	v_mfma_f32_32x32x16_bf16 v[32:47], v[0:3], v[120:123], v[32:47]
	v_add_u32_e32 v193, s8, v192
	v_bitop3_b32 v194, v59, v69, v70 bitop3:0xde
	v_add_u32_e32 v195, s8, v194
	v_bitop3_b32 v196, v68, v69, v70 bitop3:0xde
	v_add_u32_e32 v197, s8, v196
	v_lshl_add_u64 v[136:137], s[42:43], 0, v[60:61]
	v_lshl_add_u64 v[140:141], s[14:15], 0, v[52:53]
	v_mfma_f32_32x32x16_bf16 v[16:31], v[4:7], v[120:123], v[16:31]
	ds_read_b128 v[0:3], v171 offset:49152
	ds_read_b128 v[4:7], v171 offset:57344
	v_lshl_add_u64 v[138:139], s[14:15], 0, v[50:51]
	v_lshl_add_u64 v[142:143], s[14:15], 0, v[56:57]
	v_or3_b32 v138, v138, s12, v58
	v_cmp_gt_u32_e64 s[40:41], 32, v160
	s_waitcnt lgkmcnt(0)
	v_mfma_f32_32x32x16_bf16 v[32:47], v[0:3], v[116:119], v[32:47]
	v_mfma_f32_32x32x16_bf16 v[16:31], v[4:7], v[116:119], v[16:31]
	ds_read_b128 v[0:3], v173 offset:49152
	ds_read_b128 v[4:7], v173 offset:57344
	s_waitcnt lgkmcnt(0)
	v_mfma_f32_32x32x16_bf16 v[32:47], v[0:3], v[112:115], v[32:47]
	v_or_b32_e32 v0, 0x80, v184
	v_bitop3_b32 v174, v0, v8, v9 bitop3:0xde
	v_add_u32_e32 v175, 0, v174
	v_mfma_f32_32x32x16_bf16 v[16:31], v[4:7], v[112:115], v[16:31]
	ds_read_b128 v[0:3], v175 offset:49152
	ds_read_b128 v[4:7], v175 offset:57344
	s_waitcnt lgkmcnt(0)
	v_mfma_f32_32x32x16_bf16 v[32:47], v[0:3], v[108:111], v[32:47]
	v_or_b32_e32 v0, 0xa0, v184
	v_bitop3_b32 v176, v0, v8, v9 bitop3:0xde
	v_add_u32_e32 v177, 0, v176
	v_mfma_f32_32x32x16_bf16 v[16:31], v[4:7], v[108:111], v[16:31]
	ds_read_b128 v[0:3], v177 offset:49152
	ds_read_b128 v[4:7], v177 offset:57344
	s_waitcnt lgkmcnt(0)
	v_mfma_f32_32x32x16_bf16 v[32:47], v[0:3], v[104:107], v[32:47]
	v_or_b32_e32 v0, 0xc0, v184
	v_bitop3_b32 v178, v0, v8, v9 bitop3:0xde
	v_add_u32_e32 v179, 0, v178
	v_mfma_f32_32x32x16_bf16 v[16:31], v[4:7], v[104:107], v[16:31]
	ds_read_b128 v[0:3], v179 offset:49152
	ds_read_b128 v[4:7], v179 offset:57344
	s_waitcnt lgkmcnt(0)
	v_mfma_f32_32x32x16_bf16 v[32:47], v[0:3], v[100:103], v[32:47]
	v_or_b32_e32 v0, 0xe0, v184
	v_bitop3_b32 v180, v0, v8, v9 bitop3:0xde
	v_add_u32_e32 v181, 0, v180
	v_mfma_f32_32x32x16_bf16 v[16:31], v[4:7], v[100:103], v[16:31]
	ds_read_b128 v[0:3], v181 offset:49152
	ds_read_b128 v[4:7], v181 offset:57344
	s_waitcnt lgkmcnt(0)
	v_mfma_f32_32x32x16_bf16 v[32:47], v[0:3], v[96:99], v[32:47]
	v_mfma_f32_32x32x16_bf16 v[16:31], v[4:7], v[96:99], v[16:31]
	ds_read_b128 v[0:3], v183
	ds_read_b128 v[4:7], v164
	ds_read_b128 v[8:11], v183 offset:4096
	ds_read_b128 v[12:15], v164 offset:1024
	s_waitcnt lgkmcnt(0)
	v_mfma_f32_32x32x16_bf16 v[32:47], v[0:3], v[4:7], v[32:47]
	ds_read_b128 v[0:3], v193
	v_mfma_f32_32x32x16_bf16 v[16:31], v[8:11], v[4:7], v[16:31]
	ds_read_b128 v[4:7], v193 offset:4096
	v_lshlrev_b32_e32 v8, 3, v160
	s_waitcnt lgkmcnt(0)
	v_mfma_f32_32x32x16_bf16 v[32:47], v[0:3], v[12:15], v[32:47]
	v_and_b32_e32 v0, 0xc0, v64
	v_and_or_b32 v9, v8, 24, v0
	v_lshlrev_b32_e32 v0, 1, v62
	v_and_b32_e32 v10, 32, v0
	ds_read_b128 v[0:3], v195
	v_mfma_f32_32x32x16_bf16 v[16:31], v[4:7], v[12:15], v[16:31]
	v_and_b32_e32 v4, 0x100, v8
	v_or3_b32 v165, v9, v10, v4
	ds_read_b128 v[4:7], v164 offset:2048
	ds_read_b128 v[8:11], v195 offset:4096
	ds_read_b128 v[64:67], v164 offset:3072
	ds_read_b128 v[68:71], v197 offset:4096
	v_add_u32_e32 v161, s13, v165
	s_waitcnt lgkmcnt(0)
	v_mfma_f32_32x32x16_bf16 v[32:47], v[0:3], v[4:7], v[32:47]
	ds_read_b128 v[0:3], v197
	s_waitcnt vmcnt(0) lgkmcnt(0)
	s_barrier
	s_waitcnt lgkmcnt(0)
	v_mfma_f32_32x32x16_bf16 v[32:47], v[0:3], v[64:67], v[32:47]
	v_mfma_f32_32x32x16_bf16 v[16:31], v[8:11], v[4:7], v[16:31]
	s_nop 10
	v_max_f32_e32 v55, v33, v33
	v_max_f32_e32 v59, v32, v32
	v_max_f32_e32 v55, v59, v55
	v_max3_f32 v55, v55, v34, v35
	v_max3_f32 v55, v55, v36, v37
	v_max3_f32 v55, v55, v38, v39
	v_max3_f32 v55, v55, v40, v41
	v_mfma_f32_32x32x16_bf16 v[16:31], v[68:71], v[64:67], v[16:31]
	v_max3_f32 v55, v55, v42, v43
	v_max3_f32 v55, v55, v44, v45
	v_max3_f32 v55, v55, v46, v47
	v_mov_b64_e32 v[0:1], s[52:53]
	v_mov_b64_e32 v[14:15], s[66:67]
	v_mov_b64_e32 v[2:3], s[54:55]
	v_mov_b64_e32 v[4:5], s[56:57]
	s_nop 4
	v_max3_f32 v55, v55, v16, v17
	v_max3_f32 v55, v55, v18, v19
	v_max3_f32 v55, v55, v20, v21
	v_max3_f32 v55, v55, v22, v23
	v_max3_f32 v55, v55, v24, v25
	v_max3_f32 v55, v55, v26, v27
	v_max3_f32 v55, v55, v28, v29
	v_max3_f32 v55, v55, v30, v31
	v_mov_b32_e32 v59, v55
	s_nop 1
	v_permlane32_swap_b32_e32 v55, v59
	v_max_f32_e32 v59, v59, v59
	v_max_f32_e32 v55, v55, v55
	v_max_f32_e32 v55, v55, v59
	v_add_f32_e32 v59, 0x7149f2ca, v55
	v_cmp_ge_f32_e32 vcc, s97, v59
	s_cmp_eq_u64 vcc, exec
	v_max_f32_e32 v55, 0xf149f2ca, v55
	s_cselect_b64 vcc, -1, 0
	v_cndmask_b32_e32 v222, v55, v207, vcc
	v_sub_f32_e32 v59, 0xf149f2ca, v55
	v_mul_f32_e32 v64, 0xbf800000, v222
	v_mul_f32_e32 v59, 0x3f800000, v59
	v_pk_fma_f32 v[158:159], v[16:17], s[80:81], v[64:65] op_sel_hi:[1,0,0]
	v_bitop3_b32 v16, v49, 7, v62 bitop3:0x48
	v_exp_f32_e32 v59, v59
	v_mov_b32_e32 v55, v64
	v_lshl_or_b32 v136, v16, 4, v136
	v_bitop3_b32 v16, v48, 15, v62 bitop3:0x48
	v_fmamk_f32 v32, v32, 0x3f800000, v64
	v_fmamk_f32 v33, v33, 0x3f800000, v64
	v_fmamk_f32 v34, v34, 0x3f800000, v64
	v_fmamk_f32 v35, v35, 0x3f800000, v64
	v_fmamk_f32 v36, v36, 0x3f800000, v64
	v_fmamk_f32 v37, v37, 0x3f800000, v64
	v_fmamk_f32 v38, v38, 0x3f800000, v64
	v_fmamk_f32 v39, v39, 0x3f800000, v64
	v_fmamk_f32 v40, v40, 0x3f800000, v64
	v_fmamk_f32 v41, v41, 0x3f800000, v64
	v_fmamk_f32 v42, v42, 0x3f800000, v64
	v_fmamk_f32 v43, v43, 0x3f800000, v64
	v_fmamk_f32 v44, v44, 0x3f800000, v64
	v_fmamk_f32 v45, v45, 0x3f800000, v64
	v_fmamk_f32 v46, v46, 0x3f800000, v64
	v_fmac_f32_e32 v55, 0x3f800000, v47
	v_lshlrev_b32_e32 v16, 4, v16
	v_exp_f32_e32 v236, v32
	v_exp_f32_e32 v238, v33
	v_exp_f32_e32 v234, v34
	v_exp_f32_e32 v237, v35
	v_exp_f32_e32 v233, v36
	v_exp_f32_e32 v235, v37
	v_exp_f32_e32 v231, v38
	v_exp_f32_e32 v232, v39
	v_exp_f32_e32 v228, v40
	v_exp_f32_e32 v230, v41
	v_exp_f32_e32 v227, v42
	v_exp_f32_e32 v229, v43
	v_exp_f32_e32 v224, v44
	v_exp_f32_e32 v226, v45
	v_exp_f32_e32 v223, v46
	v_exp_f32_e32 v225, v55
	v_or3_b32 v140, v140, s12, v16
	v_bitop3_b32 v16, v54, 15, v62 bitop3:0x48
	v_lshlrev_b32_e32 v16, 4, v16
	v_mov_b64_e32 v[6:7], s[58:59]
	v_mov_b64_e32 v[8:9], s[60:61]
	v_mov_b64_e32 v[10:11], s[62:63]
	v_mov_b64_e32 v[12:13], s[64:65]
	v_cndmask_b32_e64 v198, v59, 1.0, vcc
	v_pk_fma_f32 v[128:129], v[30:31], s[80:81], v[64:65] op_sel_hi:[1,0,0]
	v_pk_fma_f32 v[130:131], v[28:29], s[80:81], v[64:65] op_sel_hi:[1,0,0]
	v_pk_fma_f32 v[132:133], v[26:27], s[80:81], v[64:65] op_sel_hi:[1,0,0]
	v_pk_fma_f32 v[134:135], v[24:25], s[80:81], v[64:65] op_sel_hi:[1,0,0]
	v_pk_fma_f32 v[152:153], v[22:23], s[80:81], v[64:65] op_sel_hi:[1,0,0]
	v_pk_fma_f32 v[154:155], v[20:21], s[80:81], v[64:65] op_sel_hi:[1,0,0]
	v_pk_fma_f32 v[156:157], v[18:19], s[80:81], v[64:65] op_sel_hi:[1,0,0]
	v_or3_b32 v142, v142, s12, v16
	v_mov_b64_e32 v[62:63], v[14:15]
	v_mov_b64_e32 v[46:47], v[14:15]
	v_mov_b64_e32 v[30:31], v[14:15]
	s_mov_b32 s53, 0x1b400000
	v_mov_b64_e32 v[60:61], v[12:13]
	v_mov_b64_e32 v[58:59], v[10:11]
	v_mov_b64_e32 v[56:57], v[8:9]
	v_mov_b64_e32 v[54:55], v[6:7]
	v_mov_b64_e32 v[52:53], v[4:5]
	v_mov_b64_e32 v[50:51], v[2:3]
	v_mov_b64_e32 v[48:49], v[0:1]
	v_mov_b64_e32 v[44:45], v[12:13]
	v_mov_b64_e32 v[42:43], v[10:11]
	v_mov_b64_e32 v[40:41], v[8:9]
	v_mov_b64_e32 v[38:39], v[6:7]
	v_mov_b64_e32 v[36:37], v[4:5]
	v_mov_b64_e32 v[34:35], v[2:3]
	v_mov_b64_e32 v[32:33], v[0:1]
	v_mov_b64_e32 v[28:29], v[12:13]
	v_mov_b64_e32 v[26:27], v[10:11]
	v_mov_b64_e32 v[24:25], v[8:9]
	v_mov_b64_e32 v[22:23], v[6:7]
	v_mov_b64_e32 v[20:21], v[4:5]
	v_mov_b64_e32 v[18:19], v[2:3]
	v_mov_b64_e32 v[16:17], v[0:1]
.LBB0_42:
	v_add_u32_e32 v166, 0x8000, v166
	v_add_u32_e32 v167, 0x8000, v168
	v_add_u32_e32 v168, 0x8000, v170
	v_add_u32_e32 v169, 0x8000, v172
	v_add_u32_e32 v170, 0x8000, v174
	v_add_u32_e32 v171, 0x8000, v176
	v_add_u32_e32 v172, 0x8000, v178
	v_add_u32_e32 v173, 0x8000, v180
	v_mov_b32_e32 v174, v183
	v_mov_b32_e32 v175, v193
	v_mov_b32_e32 v176, v195
	v_mov_b32_e32 v177, v197
	v_mov_b32_e32 v178, v140
	v_mov_b32_e32 v179, v142
	v_add_u32_e32 v180, 0x100, v138
	v_add_u32_e32 v181, 0x180, v138
	v_mov_b32_e32 v182, v136
	s_add_u32 s98, s74, 0x13480000
	s_addc_u32 s99, s75, 0
	s_add_u32 s100, s74, 0xae04000
	s_addc_u32 s101, s75, 0
	v_mov_b32_e32 v144, v158
	v_mov_b32_e32 v145, v159
	v_mov_b32_e32 v146, v156
	v_mov_b32_e32 v147, v157
	v_mov_b32_e32 v148, v154
	v_mov_b32_e32 v149, v155
	v_mov_b32_e32 v150, v152
	v_mov_b32_e32 v151, v153
	v_mov_b32_e32 v152, v134
	v_mov_b32_e32 v153, v135
	v_mov_b32_e32 v154, v132
	v_mov_b32_e32 v155, v133
	v_mov_b32_e32 v156, v130
	v_mov_b32_e32 v157, v131
	v_mov_b32_e32 v158, v128
	v_mov_b32_e32 v159, v129
	v_mov_b32_e32 v242, v198
	v_sub_f32_e32 v198, 0, v222
	v_sub_f32_e32 v199, 0, v222
	v_sub_f32_e32 v200, 0, v222
	v_sub_f32_e32 v201, 0, v222
	v_sub_f32_e32 v202, 0, v222
	v_sub_f32_e32 v203, 0, v222
	v_sub_f32_e32 v204, 0, v222
	v_sub_f32_e32 v205, 0, v222
	v_sub_f32_e32 v206, 0, v222
	v_sub_f32_e32 v207, 0, v222
	v_sub_f32_e32 v208, 0, v222
	v_sub_f32_e32 v209, 0, v222
	v_sub_f32_e32 v210, 0, v222
	v_sub_f32_e32 v211, 0, v222
	v_sub_f32_e32 v212, 0, v222
	v_sub_f32_e32 v213, 0, v222
	v_mov_b32_e32 v128, v236
	v_mov_b32_e32 v129, v238
	v_mov_b32_e32 v130, v234
	v_mov_b32_e32 v131, v237
	v_mov_b32_e32 v132, v233
	v_mov_b32_e32 v133, v235
	v_mov_b32_e32 v134, v231
	v_mov_b32_e32 v135, v232
	v_mov_b32_e32 v136, v228
	v_mov_b32_e32 v137, v230
	v_mov_b32_e32 v138, v227
	v_mov_b32_e32 v139, v229
	v_mov_b32_e32 v140, v224
	v_mov_b32_e32 v141, v226
	v_mov_b32_e32 v142, v223
	v_mov_b32_e32 v143, v225
	ds_read_b128 v[246:249], v164
	ds_read_b128 v[250:253], v164 offset:1024
	ds_read_b128 v[186:189], v164 offset:2048
	ds_read_b128 v[238:241], v164 offset:3072
	s_waitcnt lgkmcnt(0)
.Lmla_loop:
	ds_read_b128 v[214:217], v166 offset:32768
	ds_read_b128 v[218:221], v166 offset:40960
	ds_read_b128 v[222:225], v167 offset:32768
	ds_read_b128 v[226:229], v167 offset:40960
	ds_read_b128 v[230:233], v168 offset:32768
	ds_read_b128 v[234:237], v168 offset:40960
	v_lshl_add_u32 v183, s52, 14, v161
	s_mov_b32 m0, s45
	s_lshl_b32 s8, s49, 14
	global_load_lds_dwordx4 v178, s[98:99]
	v_exp_f32_e32 v144, v144
	v_add_f32_e32 v243, v128, v129
	v_add_f32_e32 v244, v130, v131
	v_exp_f32_e32 v145, v145
	s_waitcnt lgkmcnt(4)
	v_mfma_f32_32x32x16_bf16 v[64:79], v[214:217], v[124:127], v[198:213]
	s_mov_b32 m0, s77
	s_add_i32 s12, s8, s44
	global_load_lds_dwordx4 v179, s[98:99]
	v_cvt_pk_bf16_f32 v128, v128, v129
	v_add_f32_e32 v243, v132, v243
	v_exp_f32_e32 v146, v146
	v_mfma_f32_32x32x16_bf16 v[80:95], v[218:221], v[124:127], v[198:213]
	ds_read_b128 v[214:217], v169 offset:32768
	ds_read_b128 v[218:221], v169 offset:40960
	v_cvt_pk_bf16_f32 v129, v130, v131
	v_add_f32_e32 v244, v133, v244
	v_exp_f32_e32 v147, v147
	s_waitcnt lgkmcnt(4)
	v_mfma_f32_32x32x16_bf16 v[64:79], v[222:225], v[120:123], v[64:79]
	s_mov_b32 m0, s12
	s_add_i32 s12, s8, s47
	global_load_lds_dwordx4 v180, s[98:99]
	v_add_f32_e32 v243, v134, v243
	v_cvt_pk_bf16_f32 v130, v132, v133
	v_exp_f32_e32 v148, v148
	v_mfma_f32_32x32x16_bf16 v[80:95], v[226:229], v[120:123], v[80:95]
	ds_read_b128 v[222:225], v170 offset:32768
	ds_read_b128 v[226:229], v170 offset:40960
	v_add_f32_e32 v244, v135, v244
	v_exp_f32_e32 v149, v149
	v_add_f32_e32 v243, v136, v243
	s_waitcnt lgkmcnt(4)
	v_mfma_f32_32x32x16_bf16 v[64:79], v[230:233], v[116:119], v[64:79]
	s_mov_b32 m0, s12
	s_nop 0
	global_load_lds_dwordx4 v181, s[98:99]
	v_cvt_pk_bf16_f32 v131, v134, v135
	v_exp_f32_e32 v150, v150
	v_add_f32_e32 v244, v137, v244
	v_mfma_f32_32x32x16_bf16 v[80:95], v[234:237], v[116:119], v[80:95]
	ds_read_b128 v[230:233], v171 offset:32768
	ds_read_b128 v[234:237], v171 offset:40960
	v_exp_f32_e32 v151, v151
	v_add_f32_e32 v243, v138, v243
	v_permlane32_swap_b32_e32 v128, v130
	s_waitcnt lgkmcnt(4)
	v_mfma_f32_32x32x16_bf16 v[64:79], v[214:217], v[112:115], v[64:79]
	s_mov_b32 m0, s9
	s_nop 0
	global_load_lds_dwordx4 v182, s[100:101]
	s_add_u32 s98, s98, 0x40000
	s_addc_u32 s99, s99, 0
	s_add_u32 s100, s100, 0x2000
	s_addc_u32 s101, s101, 0
	v_cvt_pk_bf16_f32 v132, v136, v137
	v_exp_f32_e32 v152, v152
	v_add_f32_e32 v244, v139, v244
	v_mfma_f32_32x32x16_bf16 v[80:95], v[218:221], v[112:115], v[80:95]
	ds_read_b128 v[214:217], v172 offset:32768
	ds_read_b128 v[218:221], v172 offset:40960
	v_exp_f32_e32 v153, v153
	v_add_f32_e32 v243, v140, v243
	v_permlane32_swap_b32_e32 v129, v131
	s_waitcnt lgkmcnt(4)
	v_mfma_f32_32x32x16_bf16 v[64:79], v[222:225], v[108:111], v[64:79]
	v_cvt_pk_bf16_f32 v133, v138, v139
	v_add_f32_e32 v244, v141, v244
	v_exp_f32_e32 v154, v154
	v_mfma_f32_32x32x16_bf16 v[80:95], v[226:229], v[108:111], v[80:95]
	ds_read_b128 v[222:225], v173 offset:32768
	ds_read_b128 v[226:229], v173 offset:40960
	v_add_f32_e32 v243, v142, v243
	v_exp_f32_e32 v155, v155
	v_cvt_pk_bf16_f32 v134, v140, v141
	s_waitcnt lgkmcnt(4)
	v_mfma_f32_32x32x16_bf16 v[64:79], v[230:233], v[104:107], v[64:79]
	v_add_f32_e32 v244, v143, v244
	v_exp_f32_e32 v156, v156
	v_add_f32_e32 v243, v144, v243
	v_mfma_f32_32x32x16_bf16 v[80:95], v[234:237], v[104:107], v[80:95]
	ds_read_b128 v[230:233], v174 offset:8192
	ds_read_b128 v[234:237], v174 offset:12288
	v_cvt_pk_bf16_f32 v135, v142, v143
	v_exp_f32_e32 v157, v157
	v_add_f32_e32 v244, v145, v244
	s_waitcnt lgkmcnt(4)
	v_mfma_f32_32x32x16_bf16 v[64:79], v[214:217], v[100:103], v[64:79]
	v_exp_f32_e32 v158, v158
	v_add_f32_e32 v243, v146, v243
	v_permlane32_swap_b32_e32 v132, v134
	v_mfma_f32_32x32x16_bf16 v[80:95], v[218:221], v[100:103], v[80:95]
	ds_read_b128 v[214:217], v175 offset:8192
	ds_read_b128 v[218:221], v175 offset:12288
	v_cvt_pk_bf16_f32 v144, v144, v145
	v_exp_f32_e32 v159, v159
	v_add_f32_e32 v244, v147, v244
	s_waitcnt lgkmcnt(4)
	v_mfma_f32_32x32x16_bf16 v[64:79], v[222:225], v[96:99], v[64:79]
	v_add_f32_e32 v243, v148, v243
	v_permlane32_swap_b32_e32 v133, v135
	v_cvt_pk_bf16_f32 v145, v146, v147
	v_add_f32_e32 v244, v149, v244
	v_mfma_f32_32x32x16_bf16 v[80:95], v[226:229], v[96:99], v[80:95]
	ds_read_b128 v[222:225], v176 offset:8192
	ds_read_b128 v[226:229], v176 offset:12288
	v_add_f32_e32 v243, v150, v243
	v_cvt_pk_bf16_f32 v146, v148, v149
	v_add_f32_e32 v244, v151, v244
	v_add_f32_e32 v243, v152, v243
	s_waitcnt lgkmcnt(4)
	v_mfma_f32_32x32x16_bf16 v[64:79], v[230:233], v[246:249], v[64:79]
	v_cvt_pk_bf16_f32 v147, v150, v151
	v_add_f32_e32 v244, v153, v244
	v_add_f32_e32 v243, v154, v243
	v_permlane32_swap_b32_e32 v144, v146
	v_mfma_f32_32x32x16_bf16 v[80:95], v[234:237], v[246:249], v[80:95]
	ds_read_b128 v[230:233], v177 offset:8192
	ds_read_b128 v[234:237], v177 offset:12288
	v_cvt_pk_bf16_f32 v148, v152, v153
	v_add_f32_e32 v244, v155, v244
	v_add_f32_e32 v243, v156, v243
	v_permlane32_swap_b32_e32 v145, v147
	s_waitcnt lgkmcnt(4)
	v_mfma_f32_32x32x16_bf16 v[64:79], v[214:217], v[250:253], v[64:79]
	v_cvt_pk_bf16_f32 v149, v154, v155
	v_add_f32_e32 v244, v157, v244
	v_add_f32_e32 v243, v158, v243
	v_cvt_pk_bf16_f32 v150, v156, v157
	v_mfma_f32_32x32x16_bf16 v[80:95], v[218:221], v[250:253], v[80:95]
	ds_read_b64_tr_b16 v[214:215], v183
	ds_read_b64_tr_b16 v[216:217], v183 offset:2048
	ds_read_b64_tr_b16 v[218:219], v183 offset:4096
	ds_read_b64_tr_b16 v[220:221], v183 offset:6144
	v_add_f32_e32 v244, v159, v244
	v_cvt_pk_bf16_f32 v151, v158, v159
	v_permlane32_swap_b32_e32 v148, v150
	v_add_f32_e32 v243, v243, v244
	s_waitcnt lgkmcnt(6)
	v_mfma_f32_32x32x16_bf16 v[64:79], v[222:225], v[186:189], v[64:79]
	v_permlane32_swap_b32_e32 v149, v151
	v_mov_b32_e32 v244, v243
	v_mfma_f32_32x32x16_bf16 v[80:95], v[226:229], v[186:189], v[80:95]
	ds_read_b64_tr_b16 v[222:223], v183 offset:8192
	ds_read_b64_tr_b16 v[224:225], v183 offset:10240
	ds_read_b64_tr_b16 v[226:227], v183 offset:12288
	ds_read_b64_tr_b16 v[228:229], v183 offset:14336
	v_permlane32_swap_b32_e32 v243, v244
	v_add_f32_e32 v243, v243, v244
	v_fma_f32 v163, v163, v242, v243
	s_waitcnt lgkmcnt(8)
	v_mfma_f32_32x32x16_bf16 v[64:79], v[230:233], v[238:241], v[64:79]
	v_mfma_f32_32x32x16_bf16 v[80:95], v[234:237], v[238:241], v[80:95]
	s_waitcnt lgkmcnt(6)
	v_mfma_f32_32x32x16_bf16 v[0:15], v[128:131], v[214:217], v[0:15]
	ds_read_b64_tr_b16 v[136:137], v183 offset:512
	ds_read_b64_tr_b16 v[138:139], v183 offset:2560
	s_waitcnt lgkmcnt(6)
	v_mfma_f32_32x32x16_bf16 v[0:15], v[132:135], v[218:221], v[0:15]
	ds_read_b64_tr_b16 v[140:141], v183 offset:4608
	ds_read_b64_tr_b16 v[142:143], v183 offset:6656
	s_waitcnt lgkmcnt(6)
	v_mfma_f32_32x32x16_bf16 v[0:15], v[144:147], v[222:225], v[0:15]
	ds_read_b64_tr_b16 v[152:153], v183 offset:8704
	ds_read_b64_tr_b16 v[154:155], v183 offset:10752
	v_max3_f32 v196, v64, v65, v66
	v_max3_f32 v197, v80, v81, v82
	v_max3_f32 v196, v196, v67, v68
	v_max3_f32 v197, v197, v83, v84
	v_max3_f32 v196, v196, v69, v70
	v_max3_f32 v197, v197, v85, v86
	s_waitcnt lgkmcnt(6)
	v_mfma_f32_32x32x16_bf16 v[0:15], v[148:151], v[226:229], v[0:15]
	ds_read_b64_tr_b16 v[156:157], v183 offset:12800
	ds_read_b64_tr_b16 v[158:159], v183 offset:14848
	v_max3_f32 v196, v196, v71, v72
	v_max3_f32 v197, v197, v87, v88
	v_max3_f32 v196, v196, v73, v74
	v_max3_f32 v197, v197, v89, v90
	v_max3_f32 v196, v196, v75, v76
	v_max3_f32 v197, v197, v91, v92
	s_waitcnt lgkmcnt(6)
	v_mfma_f32_32x32x16_bf16 v[48:63], v[128:131], v[136:139], v[48:63]
	ds_read_b64_tr_b16 v[214:215], v183 offset:1024
	ds_read_b64_tr_b16 v[216:217], v183 offset:3072
	v_max3_f32 v196, v196, v77, v78
	v_max3_f32 v197, v197, v93, v94
	v_max_f32_e32 v196, v196, v79
	v_max_f32_e32 v197, v197, v95
	v_max_f32_e32 v196, v196, v197
	v_mov_b32_e32 v197, v196
	s_waitcnt lgkmcnt(6)
	v_mfma_f32_32x32x16_bf16 v[48:63], v[132:135], v[140:143], v[48:63]
	ds_read_b64_tr_b16 v[218:219], v183 offset:5120
	ds_read_b64_tr_b16 v[220:221], v183 offset:7168
	v_permlane32_swap_b32_e32 v196, v197
	v_max_f32_e32 v196, v196, v197
	v_cmp_ge_f32_e32 vcc, s97, v196
	s_cmp_eq_u64 vcc, exec
	s_cselect_b64 s[42:43], -1, 0
	v_mov_b32_e32 v193, 1.0
	s_mov_b64 s[12:13], 0
	s_cmp_lg_u64 s[42:43], 0
	s_cbranch_scc1 .Lmla_ok_A
	v_max_f32_e32 v197, 0, v196
	v_exp_f32_e64 v193, -v197
	v_sub_f32_e32 v64, v64, v197
	v_sub_f32_e32 v65, v65, v197
	v_sub_f32_e32 v66, v66, v197
	v_sub_f32_e32 v67, v67, v197
	v_sub_f32_e32 v68, v68, v197
	v_sub_f32_e32 v69, v69, v197
	v_sub_f32_e32 v70, v70, v197
	v_sub_f32_e32 v71, v71, v197
	v_sub_f32_e32 v72, v72, v197
	v_sub_f32_e32 v73, v73, v197
	v_sub_f32_e32 v74, v74, v197
	v_sub_f32_e32 v75, v75, v197
	v_sub_f32_e32 v76, v76, v197
	v_sub_f32_e32 v77, v77, v197
	v_sub_f32_e32 v78, v78, v197
	v_sub_f32_e32 v79, v79, v197
	v_sub_f32_e32 v80, v80, v197
	v_sub_f32_e32 v81, v81, v197
	v_sub_f32_e32 v82, v82, v197
	v_sub_f32_e32 v83, v83, v197
	v_sub_f32_e32 v84, v84, v197
	v_sub_f32_e32 v85, v85, v197
	v_sub_f32_e32 v86, v86, v197
	v_sub_f32_e32 v87, v87, v197
	v_sub_f32_e32 v88, v88, v197
	v_sub_f32_e32 v89, v89, v197
	v_sub_f32_e32 v90, v90, v197
	v_sub_f32_e32 v91, v91, v197
	v_sub_f32_e32 v92, v92, v197
	v_sub_f32_e32 v93, v93, v197
	v_sub_f32_e32 v94, v94, v197
	v_sub_f32_e32 v95, v95, v197
	v_sub_f32_e32 v198, v198, v197
	v_sub_f32_e32 v199, v199, v197
	v_sub_f32_e32 v200, v200, v197
	v_sub_f32_e32 v201, v201, v197
	v_sub_f32_e32 v202, v202, v197
	v_sub_f32_e32 v203, v203, v197
	v_sub_f32_e32 v204, v204, v197
	v_sub_f32_e32 v205, v205, v197
	v_sub_f32_e32 v206, v206, v197
	v_sub_f32_e32 v207, v207, v197
	v_sub_f32_e32 v208, v208, v197
	v_sub_f32_e32 v209, v209, v197
	v_sub_f32_e32 v210, v210, v197
	v_sub_f32_e32 v211, v211, v197
	v_sub_f32_e32 v212, v212, v197
	v_sub_f32_e32 v213, v213, v197
	v_cmp_gt_f32_e64 s[12:13], 1.0, v193
.Lmla_ok_A:
	s_waitcnt lgkmcnt(6)
	v_mfma_f32_32x32x16_bf16 v[48:63], v[144:147], v[152:155], v[48:63]
	ds_read_b64_tr_b16 v[222:223], v183 offset:9216
	ds_read_b64_tr_b16 v[224:225], v183 offset:11264
	v_exp_f32_e32 v64, v64
	v_exp_f32_e32 v65, v65
	v_exp_f32_e32 v66, v66
	s_waitcnt lgkmcnt(6)
	v_mfma_f32_32x32x16_bf16 v[48:63], v[148:151], v[156:159], v[48:63]
	ds_read_b64_tr_b16 v[226:227], v183 offset:13312
	ds_read_b64_tr_b16 v[228:229], v183 offset:15360
	v_exp_f32_e32 v67, v67
	v_exp_f32_e32 v68, v68
	v_exp_f32_e32 v69, v69
	s_waitcnt lgkmcnt(6)
	v_mfma_f32_32x32x16_bf16 v[32:47], v[128:131], v[214:217], v[32:47]
	ds_read_b64_tr_b16 v[136:137], v183 offset:1536
	ds_read_b64_tr_b16 v[138:139], v183 offset:3584
	v_exp_f32_e32 v70, v70
	v_exp_f32_e32 v71, v71
	v_exp_f32_e32 v72, v72
	s_waitcnt lgkmcnt(6)
	v_mfma_f32_32x32x16_bf16 v[32:47], v[132:135], v[218:221], v[32:47]
	ds_read_b64_tr_b16 v[140:141], v183 offset:5632
	ds_read_b64_tr_b16 v[142:143], v183 offset:7680
	v_exp_f32_e32 v73, v73
	v_exp_f32_e32 v74, v74
	v_exp_f32_e32 v75, v75
	s_waitcnt lgkmcnt(6)
	v_mfma_f32_32x32x16_bf16 v[32:47], v[144:147], v[222:225], v[32:47]
	ds_read_b64_tr_b16 v[152:153], v183 offset:9728
	ds_read_b64_tr_b16 v[154:155], v183 offset:11776
	v_exp_f32_e32 v76, v76
	v_exp_f32_e32 v77, v77
	v_exp_f32_e32 v78, v78
	s_waitcnt lgkmcnt(6)
	v_mfma_f32_32x32x16_bf16 v[32:47], v[148:151], v[226:229], v[32:47]
	ds_read_b64_tr_b16 v[156:157], v183 offset:13824
	ds_read_b64_tr_b16 v[158:159], v183 offset:15872
	v_exp_f32_e32 v79, v79
	s_waitcnt lgkmcnt(6)
	v_mfma_f32_32x32x16_bf16 v[16:31], v[128:131], v[136:139], v[16:31]
	s_waitcnt lgkmcnt(4)
	v_mfma_f32_32x32x16_bf16 v[16:31], v[132:135], v[140:143], v[16:31]
	s_waitcnt lgkmcnt(2)
	v_mfma_f32_32x32x16_bf16 v[16:31], v[144:147], v[152:155], v[16:31]
	s_waitcnt lgkmcnt(0)
	v_mfma_f32_32x32x16_bf16 v[16:31], v[148:151], v[156:159], v[16:31]
	s_cmp_lg_u64 s[12:13], 0
	s_cbranch_scc0 .Lmla_nors_A
	s_and_saveexec_b64 s[20:21], s[40:41]
	ds_write_b32 v162, v193 offset:128
	s_or_b64 exec, exec, s[20:21]
	s_waitcnt lgkmcnt(0)
	v_add_u32_e32 v245, s37, v184
	ds_read_b128 v[214:217], v245 offset:128
	ds_read_b128 v[218:221], v245 offset:160
	ds_read_b128 v[222:225], v245 offset:192
	ds_read_b128 v[226:229], v245 offset:224
	s_waitcnt lgkmcnt(0)
	v_pk_mul_f32 v[0:1], v[0:1], v[214:215]
	v_pk_mul_f32 v[2:3], v[2:3], v[216:217]
	v_pk_mul_f32 v[4:5], v[4:5], v[218:219]
	v_pk_mul_f32 v[6:7], v[6:7], v[220:221]
	v_pk_mul_f32 v[8:9], v[8:9], v[222:223]
	v_pk_mul_f32 v[10:11], v[10:11], v[224:225]
	v_pk_mul_f32 v[12:13], v[12:13], v[226:227]
	v_pk_mul_f32 v[14:15], v[14:15], v[228:229]
	v_pk_mul_f32 v[48:49], v[48:49], v[214:215]
	v_pk_mul_f32 v[50:51], v[50:51], v[216:217]
	v_pk_mul_f32 v[52:53], v[52:53], v[218:219]
	v_pk_mul_f32 v[54:55], v[54:55], v[220:221]
	v_pk_mul_f32 v[56:57], v[56:57], v[222:223]
	v_pk_mul_f32 v[58:59], v[58:59], v[224:225]
	v_pk_mul_f32 v[60:61], v[60:61], v[226:227]
	v_pk_mul_f32 v[62:63], v[62:63], v[228:229]
	v_pk_mul_f32 v[32:33], v[32:33], v[214:215]
	v_pk_mul_f32 v[34:35], v[34:35], v[216:217]
	v_pk_mul_f32 v[36:37], v[36:37], v[218:219]
	v_pk_mul_f32 v[38:39], v[38:39], v[220:221]
	v_pk_mul_f32 v[40:41], v[40:41], v[222:223]
	v_pk_mul_f32 v[42:43], v[42:43], v[224:225]
	v_pk_mul_f32 v[44:45], v[44:45], v[226:227]
	v_pk_mul_f32 v[46:47], v[46:47], v[228:229]
	v_pk_mul_f32 v[16:17], v[16:17], v[214:215]
	v_pk_mul_f32 v[18:19], v[18:19], v[216:217]
	v_pk_mul_f32 v[20:21], v[20:21], v[218:219]
	v_pk_mul_f32 v[22:23], v[22:23], v[220:221]
	v_pk_mul_f32 v[24:25], v[24:25], v[222:223]
	v_pk_mul_f32 v[26:27], v[26:27], v[224:225]
	v_pk_mul_f32 v[28:29], v[28:29], v[226:227]
	v_pk_mul_f32 v[30:31], v[30:31], v[228:229]
.Lmla_nors_A:
	s_add_i32 s8, s52, 1
	s_cmp_lg_u32 s52, 2
	s_cselect_b32 s14, s8, 0
	s_add_i32 s8, s49, 1
	s_cmp_lg_u32 s49, 2
	s_cselect_b32 s15, s8, 0
	s_waitcnt vmcnt(0) lgkmcnt(0)
	s_barrier
	ds_read_b128 v[214:217], v166 offset:16384
	ds_read_b128 v[218:221], v166 offset:24576
	ds_read_b128 v[222:225], v167 offset:16384
	ds_read_b128 v[226:229], v167 offset:24576
	ds_read_b128 v[230:233], v168 offset:16384
	ds_read_b128 v[234:237], v168 offset:24576
	v_lshl_add_u32 v183, s14, 14, v161
	s_mov_b32 m0, s93
	s_lshl_b32 s8, s15, 14
	global_load_lds_dwordx4 v178, s[98:99]
	v_exp_f32_e32 v80, v80
	v_add_f32_e32 v243, v64, v65
	v_add_f32_e32 v244, v66, v67
	v_exp_f32_e32 v81, v81
	s_waitcnt lgkmcnt(4)
	v_mfma_f32_32x32x16_bf16 v[128:143], v[214:217], v[124:127], v[198:213]
	s_mov_b32 m0, s50
	s_add_i32 s12, s8, s44
	global_load_lds_dwordx4 v179, s[98:99]
	v_cvt_pk_bf16_f32 v64, v64, v65
	v_add_f32_e32 v243, v68, v243
	v_exp_f32_e32 v82, v82
	v_mfma_f32_32x32x16_bf16 v[144:159], v[218:221], v[124:127], v[198:213]
	ds_read_b128 v[214:217], v169 offset:16384
	ds_read_b128 v[218:221], v169 offset:24576
	v_cvt_pk_bf16_f32 v65, v66, v67
	v_add_f32_e32 v244, v69, v244
	v_exp_f32_e32 v83, v83
	s_waitcnt lgkmcnt(4)
	v_mfma_f32_32x32x16_bf16 v[128:143], v[222:225], v[120:123], v[128:143]
	s_mov_b32 m0, s12
	s_add_i32 s12, s8, s47
	global_load_lds_dwordx4 v180, s[98:99]
	v_add_f32_e32 v243, v70, v243
	v_cvt_pk_bf16_f32 v66, v68, v69
	v_exp_f32_e32 v84, v84
	v_mfma_f32_32x32x16_bf16 v[144:159], v[226:229], v[120:123], v[144:159]
	ds_read_b128 v[222:225], v170 offset:16384
	ds_read_b128 v[226:229], v170 offset:24576
	v_add_f32_e32 v244, v71, v244
	v_exp_f32_e32 v85, v85
	v_add_f32_e32 v243, v72, v243
	s_waitcnt lgkmcnt(4)
	v_mfma_f32_32x32x16_bf16 v[128:143], v[230:233], v[116:119], v[128:143]
	s_mov_b32 m0, s12
	s_nop 0
	global_load_lds_dwordx4 v181, s[98:99]
	v_cvt_pk_bf16_f32 v67, v70, v71
	v_exp_f32_e32 v86, v86
	v_add_f32_e32 v244, v73, v244
	v_mfma_f32_32x32x16_bf16 v[144:159], v[234:237], v[116:119], v[144:159]
	ds_read_b128 v[230:233], v171 offset:16384
	ds_read_b128 v[234:237], v171 offset:24576
	v_exp_f32_e32 v87, v87
	v_add_f32_e32 v243, v74, v243
	v_permlane32_swap_b32_e32 v64, v66
	s_waitcnt lgkmcnt(4)
	v_mfma_f32_32x32x16_bf16 v[128:143], v[214:217], v[112:115], v[128:143]
	s_mov_b32 m0, s51
	s_nop 0
	global_load_lds_dwordx4 v182, s[100:101]
	s_add_u32 s98, s98, 0x40000
	s_addc_u32 s99, s99, 0
	s_add_u32 s100, s100, 0x2000
	s_addc_u32 s101, s101, 0
	v_cvt_pk_bf16_f32 v68, v72, v73
	v_exp_f32_e32 v88, v88
	v_add_f32_e32 v244, v75, v244
	v_mfma_f32_32x32x16_bf16 v[144:159], v[218:221], v[112:115], v[144:159]
	ds_read_b128 v[214:217], v172 offset:16384
	ds_read_b128 v[218:221], v172 offset:24576
	v_exp_f32_e32 v89, v89
	v_add_f32_e32 v243, v76, v243
	v_permlane32_swap_b32_e32 v65, v67
	s_waitcnt lgkmcnt(4)
	v_mfma_f32_32x32x16_bf16 v[128:143], v[222:225], v[108:111], v[128:143]
	v_cvt_pk_bf16_f32 v69, v74, v75
	v_add_f32_e32 v244, v77, v244
	v_exp_f32_e32 v90, v90
	v_mfma_f32_32x32x16_bf16 v[144:159], v[226:229], v[108:111], v[144:159]
	ds_read_b128 v[222:225], v173 offset:16384
	ds_read_b128 v[226:229], v173 offset:24576
	v_add_f32_e32 v243, v78, v243
	v_exp_f32_e32 v91, v91
	v_cvt_pk_bf16_f32 v70, v76, v77
	s_waitcnt lgkmcnt(4)
	v_mfma_f32_32x32x16_bf16 v[128:143], v[230:233], v[104:107], v[128:143]
	v_add_f32_e32 v244, v79, v244
	v_exp_f32_e32 v92, v92
	v_add_f32_e32 v243, v80, v243
	v_mfma_f32_32x32x16_bf16 v[144:159], v[234:237], v[104:107], v[144:159]
	ds_read_b128 v[230:233], v174
	ds_read_b128 v[234:237], v174 offset:4096
	v_cvt_pk_bf16_f32 v71, v78, v79
	v_exp_f32_e32 v93, v93
	v_add_f32_e32 v244, v81, v244
	s_waitcnt lgkmcnt(4)
	v_mfma_f32_32x32x16_bf16 v[128:143], v[214:217], v[100:103], v[128:143]
	v_exp_f32_e32 v94, v94
	v_add_f32_e32 v243, v82, v243
	v_permlane32_swap_b32_e32 v68, v70
	v_mfma_f32_32x32x16_bf16 v[144:159], v[218:221], v[100:103], v[144:159]
	ds_read_b128 v[214:217], v175
	ds_read_b128 v[218:221], v175 offset:4096
	v_cvt_pk_bf16_f32 v80, v80, v81
	v_exp_f32_e32 v95, v95
	v_add_f32_e32 v244, v83, v244
	s_waitcnt lgkmcnt(4)
	v_mfma_f32_32x32x16_bf16 v[128:143], v[222:225], v[96:99], v[128:143]
	v_add_f32_e32 v243, v84, v243
	v_permlane32_swap_b32_e32 v69, v71
	v_cvt_pk_bf16_f32 v81, v82, v83
	v_add_f32_e32 v244, v85, v244
	v_mfma_f32_32x32x16_bf16 v[144:159], v[226:229], v[96:99], v[144:159]
	ds_read_b128 v[222:225], v176
	ds_read_b128 v[226:229], v176 offset:4096
	v_add_f32_e32 v243, v86, v243
	v_cvt_pk_bf16_f32 v82, v84, v85
	v_add_f32_e32 v244, v87, v244
	v_add_f32_e32 v243, v88, v243
	s_waitcnt lgkmcnt(4)
	v_mfma_f32_32x32x16_bf16 v[128:143], v[230:233], v[246:249], v[128:143]
	v_cvt_pk_bf16_f32 v83, v86, v87
	v_add_f32_e32 v244, v89, v244
	v_add_f32_e32 v243, v90, v243
	v_permlane32_swap_b32_e32 v80, v82
	v_mfma_f32_32x32x16_bf16 v[144:159], v[234:237], v[246:249], v[144:159]
	ds_read_b128 v[230:233], v177
	ds_read_b128 v[234:237], v177 offset:4096
	v_cvt_pk_bf16_f32 v84, v88, v89
	v_add_f32_e32 v244, v91, v244
	v_add_f32_e32 v243, v92, v243
	v_permlane32_swap_b32_e32 v81, v83
	s_waitcnt lgkmcnt(4)
	v_mfma_f32_32x32x16_bf16 v[128:143], v[214:217], v[250:253], v[128:143]
	v_cvt_pk_bf16_f32 v85, v90, v91
	v_add_f32_e32 v244, v93, v244
	v_add_f32_e32 v243, v94, v243
	v_cvt_pk_bf16_f32 v86, v92, v93
	v_mfma_f32_32x32x16_bf16 v[144:159], v[218:221], v[250:253], v[144:159]
	ds_read_b64_tr_b16 v[214:215], v183
	ds_read_b64_tr_b16 v[216:217], v183 offset:2048
	ds_read_b64_tr_b16 v[218:219], v183 offset:4096
	ds_read_b64_tr_b16 v[220:221], v183 offset:6144
	v_add_f32_e32 v244, v95, v244
	v_cvt_pk_bf16_f32 v87, v94, v95
	v_permlane32_swap_b32_e32 v84, v86
	v_add_f32_e32 v243, v243, v244
	s_waitcnt lgkmcnt(6)
	v_mfma_f32_32x32x16_bf16 v[128:143], v[222:225], v[186:189], v[128:143]
	v_permlane32_swap_b32_e32 v85, v87
	v_mov_b32_e32 v244, v243
	v_mfma_f32_32x32x16_bf16 v[144:159], v[226:229], v[186:189], v[144:159]
	ds_read_b64_tr_b16 v[222:223], v183 offset:8192
	ds_read_b64_tr_b16 v[224:225], v183 offset:10240
	ds_read_b64_tr_b16 v[226:227], v183 offset:12288
	ds_read_b64_tr_b16 v[228:229], v183 offset:14336
	v_permlane32_swap_b32_e32 v243, v244
	v_add_f32_e32 v243, v243, v244
	v_fma_f32 v163, v163, v193, v243
	s_waitcnt lgkmcnt(8)
	v_mfma_f32_32x32x16_bf16 v[128:143], v[230:233], v[238:241], v[128:143]
	v_mfma_f32_32x32x16_bf16 v[144:159], v[234:237], v[238:241], v[144:159]
	s_waitcnt lgkmcnt(6)
	v_mfma_f32_32x32x16_bf16 v[0:15], v[64:67], v[214:217], v[0:15]
	ds_read_b64_tr_b16 v[72:73], v183 offset:512
	ds_read_b64_tr_b16 v[74:75], v183 offset:2560
	s_waitcnt lgkmcnt(6)
	v_mfma_f32_32x32x16_bf16 v[0:15], v[68:71], v[218:221], v[0:15]
	ds_read_b64_tr_b16 v[76:77], v183 offset:4608
	ds_read_b64_tr_b16 v[78:79], v183 offset:6656
	s_waitcnt lgkmcnt(6)
	v_mfma_f32_32x32x16_bf16 v[0:15], v[80:83], v[222:225], v[0:15]
	ds_read_b64_tr_b16 v[88:89], v183 offset:8704
	ds_read_b64_tr_b16 v[90:91], v183 offset:10752
	v_max3_f32 v196, v128, v129, v130
	v_max3_f32 v197, v144, v145, v146
	v_max3_f32 v196, v196, v131, v132
	v_max3_f32 v197, v197, v147, v148
	v_max3_f32 v196, v196, v133, v134
	v_max3_f32 v197, v197, v149, v150
	s_waitcnt lgkmcnt(6)
	v_mfma_f32_32x32x16_bf16 v[0:15], v[84:87], v[226:229], v[0:15]
	ds_read_b64_tr_b16 v[92:93], v183 offset:12800
	ds_read_b64_tr_b16 v[94:95], v183 offset:14848
	v_max3_f32 v196, v196, v135, v136
	v_max3_f32 v197, v197, v151, v152
	v_max3_f32 v196, v196, v137, v138
	v_max3_f32 v197, v197, v153, v154
	v_max3_f32 v196, v196, v139, v140
	v_max3_f32 v197, v197, v155, v156
	s_waitcnt lgkmcnt(6)
	v_mfma_f32_32x32x16_bf16 v[48:63], v[64:67], v[72:75], v[48:63]
	ds_read_b64_tr_b16 v[214:215], v183 offset:1024
	ds_read_b64_tr_b16 v[216:217], v183 offset:3072
	v_max3_f32 v196, v196, v141, v142
	v_max3_f32 v197, v197, v157, v158
	v_max_f32_e32 v196, v196, v143
	v_max_f32_e32 v197, v197, v159
	v_max_f32_e32 v196, v196, v197
	v_mov_b32_e32 v197, v196
	s_waitcnt lgkmcnt(6)
	v_mfma_f32_32x32x16_bf16 v[48:63], v[68:71], v[76:79], v[48:63]
	ds_read_b64_tr_b16 v[218:219], v183 offset:5120
	ds_read_b64_tr_b16 v[220:221], v183 offset:7168
	v_permlane32_swap_b32_e32 v196, v197
	v_max_f32_e32 v196, v196, v197
	v_cmp_ge_f32_e32 vcc, s97, v196
	s_cmp_eq_u64 vcc, exec
	s_cselect_b64 s[42:43], -1, 0
	v_mov_b32_e32 v242, 1.0
	s_mov_b64 s[12:13], 0
	s_cmp_lg_u64 s[42:43], 0
	s_cbranch_scc1 .Lmla_ok_B
	v_max_f32_e32 v197, 0, v196
	v_exp_f32_e64 v242, -v197
	v_sub_f32_e32 v128, v128, v197
	v_sub_f32_e32 v129, v129, v197
	v_sub_f32_e32 v130, v130, v197
	v_sub_f32_e32 v131, v131, v197
	v_sub_f32_e32 v132, v132, v197
	v_sub_f32_e32 v133, v133, v197
	v_sub_f32_e32 v134, v134, v197
	v_sub_f32_e32 v135, v135, v197
	v_sub_f32_e32 v136, v136, v197
	v_sub_f32_e32 v137, v137, v197
	v_sub_f32_e32 v138, v138, v197
	v_sub_f32_e32 v139, v139, v197
	v_sub_f32_e32 v140, v140, v197
	v_sub_f32_e32 v141, v141, v197
	v_sub_f32_e32 v142, v142, v197
	v_sub_f32_e32 v143, v143, v197
	v_sub_f32_e32 v144, v144, v197
	v_sub_f32_e32 v145, v145, v197
	v_sub_f32_e32 v146, v146, v197
	v_sub_f32_e32 v147, v147, v197
	v_sub_f32_e32 v148, v148, v197
	v_sub_f32_e32 v149, v149, v197
	v_sub_f32_e32 v150, v150, v197
	v_sub_f32_e32 v151, v151, v197
	v_sub_f32_e32 v152, v152, v197
	v_sub_f32_e32 v153, v153, v197
	v_sub_f32_e32 v154, v154, v197
	v_sub_f32_e32 v155, v155, v197
	v_sub_f32_e32 v156, v156, v197
	v_sub_f32_e32 v157, v157, v197
	v_sub_f32_e32 v158, v158, v197
	v_sub_f32_e32 v159, v159, v197
	v_sub_f32_e32 v198, v198, v197
	v_sub_f32_e32 v199, v199, v197
	v_sub_f32_e32 v200, v200, v197
	v_sub_f32_e32 v201, v201, v197
	v_sub_f32_e32 v202, v202, v197
	v_sub_f32_e32 v203, v203, v197
	v_sub_f32_e32 v204, v204, v197
	v_sub_f32_e32 v205, v205, v197
	v_sub_f32_e32 v206, v206, v197
	v_sub_f32_e32 v207, v207, v197
	v_sub_f32_e32 v208, v208, v197
	v_sub_f32_e32 v209, v209, v197
	v_sub_f32_e32 v210, v210, v197
	v_sub_f32_e32 v211, v211, v197
	v_sub_f32_e32 v212, v212, v197
	v_sub_f32_e32 v213, v213, v197
	v_cmp_gt_f32_e64 s[12:13], 1.0, v242
.Lmla_ok_B:
	s_waitcnt lgkmcnt(6)
	v_mfma_f32_32x32x16_bf16 v[48:63], v[80:83], v[88:91], v[48:63]
	ds_read_b64_tr_b16 v[222:223], v183 offset:9216
	ds_read_b64_tr_b16 v[224:225], v183 offset:11264
	v_exp_f32_e32 v128, v128
	v_exp_f32_e32 v129, v129
	v_exp_f32_e32 v130, v130
	s_waitcnt lgkmcnt(6)
	v_mfma_f32_32x32x16_bf16 v[48:63], v[84:87], v[92:95], v[48:63]
	ds_read_b64_tr_b16 v[226:227], v183 offset:13312
	ds_read_b64_tr_b16 v[228:229], v183 offset:15360
	v_exp_f32_e32 v131, v131
	v_exp_f32_e32 v132, v132
	v_exp_f32_e32 v133, v133
	s_waitcnt lgkmcnt(6)
	v_mfma_f32_32x32x16_bf16 v[32:47], v[64:67], v[214:217], v[32:47]
	ds_read_b64_tr_b16 v[72:73], v183 offset:1536
	ds_read_b64_tr_b16 v[74:75], v183 offset:3584
	v_exp_f32_e32 v134, v134
	v_exp_f32_e32 v135, v135
	v_exp_f32_e32 v136, v136
	s_waitcnt lgkmcnt(6)
	v_mfma_f32_32x32x16_bf16 v[32:47], v[68:71], v[218:221], v[32:47]
	ds_read_b64_tr_b16 v[76:77], v183 offset:5632
	ds_read_b64_tr_b16 v[78:79], v183 offset:7680
	v_exp_f32_e32 v137, v137
	v_exp_f32_e32 v138, v138
	v_exp_f32_e32 v139, v139
	s_waitcnt lgkmcnt(6)
	v_mfma_f32_32x32x16_bf16 v[32:47], v[80:83], v[222:225], v[32:47]
	ds_read_b64_tr_b16 v[88:89], v183 offset:9728
	ds_read_b64_tr_b16 v[90:91], v183 offset:11776
	v_exp_f32_e32 v140, v140
	v_exp_f32_e32 v141, v141
	v_exp_f32_e32 v142, v142
	s_waitcnt lgkmcnt(6)
	v_mfma_f32_32x32x16_bf16 v[32:47], v[84:87], v[226:229], v[32:47]
	ds_read_b64_tr_b16 v[92:93], v183 offset:13824
	ds_read_b64_tr_b16 v[94:95], v183 offset:15872
	v_exp_f32_e32 v143, v143
	s_waitcnt lgkmcnt(6)
	v_mfma_f32_32x32x16_bf16 v[16:31], v[64:67], v[72:75], v[16:31]
	s_waitcnt lgkmcnt(4)
	v_mfma_f32_32x32x16_bf16 v[16:31], v[68:71], v[76:79], v[16:31]
	s_waitcnt lgkmcnt(2)
	v_mfma_f32_32x32x16_bf16 v[16:31], v[80:83], v[88:91], v[16:31]
	s_waitcnt lgkmcnt(0)
	v_mfma_f32_32x32x16_bf16 v[16:31], v[84:87], v[92:95], v[16:31]
	s_cmp_lg_u64 s[12:13], 0
	s_cbranch_scc0 .Lmla_nors_B
	s_and_saveexec_b64 s[20:21], s[40:41]
	ds_write_b32 v162, v242 offset:128
	s_or_b64 exec, exec, s[20:21]
	s_waitcnt lgkmcnt(0)
	v_add_u32_e32 v245, s37, v184
	ds_read_b128 v[214:217], v245 offset:128
	ds_read_b128 v[218:221], v245 offset:160
	ds_read_b128 v[222:225], v245 offset:192
	ds_read_b128 v[226:229], v245 offset:224
	s_waitcnt lgkmcnt(0)
	v_pk_mul_f32 v[0:1], v[0:1], v[214:215]
	v_pk_mul_f32 v[2:3], v[2:3], v[216:217]
	v_pk_mul_f32 v[4:5], v[4:5], v[218:219]
	v_pk_mul_f32 v[6:7], v[6:7], v[220:221]
	v_pk_mul_f32 v[8:9], v[8:9], v[222:223]
	v_pk_mul_f32 v[10:11], v[10:11], v[224:225]
	v_pk_mul_f32 v[12:13], v[12:13], v[226:227]
	v_pk_mul_f32 v[14:15], v[14:15], v[228:229]
	v_pk_mul_f32 v[48:49], v[48:49], v[214:215]
	v_pk_mul_f32 v[50:51], v[50:51], v[216:217]
	v_pk_mul_f32 v[52:53], v[52:53], v[218:219]
	v_pk_mul_f32 v[54:55], v[54:55], v[220:221]
	v_pk_mul_f32 v[56:57], v[56:57], v[222:223]
	v_pk_mul_f32 v[58:59], v[58:59], v[224:225]
	v_pk_mul_f32 v[60:61], v[60:61], v[226:227]
	v_pk_mul_f32 v[62:63], v[62:63], v[228:229]
	v_pk_mul_f32 v[32:33], v[32:33], v[214:215]
	v_pk_mul_f32 v[34:35], v[34:35], v[216:217]
	v_pk_mul_f32 v[36:37], v[36:37], v[218:219]
	v_pk_mul_f32 v[38:39], v[38:39], v[220:221]
	v_pk_mul_f32 v[40:41], v[40:41], v[222:223]
	v_pk_mul_f32 v[42:43], v[42:43], v[224:225]
	v_pk_mul_f32 v[44:45], v[44:45], v[226:227]
	v_pk_mul_f32 v[46:47], v[46:47], v[228:229]
	v_pk_mul_f32 v[16:17], v[16:17], v[214:215]
	v_pk_mul_f32 v[18:19], v[18:19], v[216:217]
	v_pk_mul_f32 v[20:21], v[20:21], v[218:219]
	v_pk_mul_f32 v[22:23], v[22:23], v[220:221]
	v_pk_mul_f32 v[24:25], v[24:25], v[222:223]
	v_pk_mul_f32 v[26:27], v[26:27], v[224:225]
	v_pk_mul_f32 v[28:29], v[28:29], v[226:227]
	v_pk_mul_f32 v[30:31], v[30:31], v[228:229]
.Lmla_nors_B:
	s_add_i32 s8, s14, 1
	s_cmp_lg_u32 s14, 2
	s_cselect_b32 s52, s8, 0
	s_add_i32 s8, s15, 1
	s_cmp_lg_u32 s15, 2
	s_cselect_b32 s49, s8, 0
	s_waitcnt vmcnt(0) lgkmcnt(0)
	s_barrier
	s_add_i32 s48, s48, 2
	s_cmp_lt_u32 s48, 61
	s_cbranch_scc1 .Lmla_loop
	v_mov_b32_e32 v236, v128
	v_mov_b32_e32 v238, v129
	v_mov_b32_e32 v234, v130
	v_mov_b32_e32 v237, v131
	v_mov_b32_e32 v233, v132
	v_mov_b32_e32 v235, v133
	v_mov_b32_e32 v231, v134
	v_mov_b32_e32 v232, v135
	v_mov_b32_e32 v228, v136
	v_mov_b32_e32 v230, v137
	v_mov_b32_e32 v227, v138
	v_mov_b32_e32 v229, v139
	v_mov_b32_e32 v224, v140
	v_mov_b32_e32 v226, v141
	v_mov_b32_e32 v223, v142
	v_mov_b32_e32 v225, v143
	v_mov_b32_e32 v134, v152
	v_mov_b32_e32 v135, v153
	v_mov_b32_e32 v132, v154
	v_mov_b32_e32 v133, v155
	v_mov_b32_e32 v130, v156
	v_mov_b32_e32 v131, v157
	v_mov_b32_e32 v128, v158
	v_mov_b32_e32 v129, v159
	v_mov_b32_e32 v158, v144
	v_mov_b32_e32 v159, v145
	v_mov_b32_e32 v156, v146
	v_mov_b32_e32 v157, v147
	v_mov_b32_e32 v154, v148
	v_mov_b32_e32 v155, v149
	v_mov_b32_e32 v152, v150
	v_mov_b32_e32 v153, v151
	v_sub_f32_e32 v222, 0, v198
	v_mov_b32_e32 v144, v242
	v_mov_b32_e32 v198, v242
	v_add_u32_e32 v199, 0x8000, v166
	v_add_u32_e32 v200, 0x8000, v167
	v_add_u32_e32 v201, 0x8000, v168
	v_add_u32_e32 v202, 0x8000, v169
	v_add_u32_e32 v214, 0x8000, v170
	v_add_u32_e32 v215, 0x8000, v171
	v_add_u32_e32 v216, 0x8000, v172
	v_add_u32_e32 v217, 0x8000, v173
	v_add_u32_e32 v219, 0x2000, v174
	v_add_u32_e32 v218, 0x2000, v175
	v_add_u32_e32 v220, 0x2000, v176
	v_add_u32_e32 v221, 0x2000, v177
	v_mov_b32_e32 v203, v191
	v_mov_b32_e32 v204, 0x358637bd
	v_mov_b32_e32 v205, 0x260
	v_mov_b32_e32 v206, 1
	v_mov_b32_e32 v207, 0xf149f2ca
	v_mbcnt_lo_u32_b32 v208, -1, 0
	v_mbcnt_hi_u32_b32 v208, -1, v208
	v_mov_b32_e32 v209, 0x1450
	v_mov_b64_e32 v[210:211], 0x400
	v_mov_b32_e32 v212, 0x1c70
	v_and_b32_e32 v213, 63, v191
	v_mov_b32_e32 v242, 0
	v_mov_b32_e32 v243, 0
	v_mov_b32_e32 v244, 0
	v_mov_b32_e32 v245, 0
.LBB0_52:
	ds_read_b128 v[64:67], v199
	ds_read_b128 v[68:71], v199 offset:8192
	s_waitcnt lgkmcnt(0)
	v_mfma_f32_32x32x16_bf16 v[80:95], v[64:67], v[124:127], 0
	v_mfma_f32_32x32x16_bf16 v[64:79], v[68:71], v[124:127], 0
	ds_read_b128 v[124:127], v200
	ds_read_b128 v[136:139], v200 offset:8192
	s_waitcnt lgkmcnt(0)
	v_mfma_f32_32x32x16_bf16 v[80:95], v[124:127], v[120:123], v[80:95]
	v_mfma_f32_32x32x16_bf16 v[64:79], v[136:139], v[120:123], v[64:79]
	ds_read_b128 v[120:123], v201
	ds_read_b128 v[124:127], v201 offset:8192
	s_waitcnt lgkmcnt(0)
	v_mfma_f32_32x32x16_bf16 v[80:95], v[120:123], v[116:119], v[80:95]
	v_mfma_f32_32x32x16_bf16 v[64:79], v[124:127], v[116:119], v[64:79]
	ds_read_b128 v[116:119], v202
	ds_read_b128 v[120:123], v202 offset:8192
	s_waitcnt lgkmcnt(0)
	v_mfma_f32_32x32x16_bf16 v[80:95], v[116:119], v[112:115], v[80:95]
	v_mfma_f32_32x32x16_bf16 v[64:79], v[120:123], v[112:115], v[64:79]
	ds_read_b128 v[112:115], v214
	ds_read_b128 v[116:119], v214 offset:8192
	v_exp_f32_e32 v120, v128
	v_exp_f32_e32 v121, v129
	s_waitcnt lgkmcnt(0)
	v_mfma_f32_32x32x16_bf16 v[80:95], v[112:115], v[108:111], v[80:95]
	v_mfma_f32_32x32x16_bf16 v[64:79], v[116:119], v[108:111], v[64:79]
	ds_read_b128 v[108:111], v215
	ds_read_b128 v[112:115], v215 offset:8192
	v_exp_f32_e32 v116, v132
	v_exp_f32_e32 v117, v133
	v_exp_f32_e32 v118, v130
	v_exp_f32_e32 v119, v131
	s_waitcnt lgkmcnt(0)
	v_mfma_f32_32x32x16_bf16 v[80:95], v[108:111], v[104:107], v[80:95]
	v_mfma_f32_32x32x16_bf16 v[64:79], v[112:115], v[104:107], v[64:79]
	ds_read_b128 v[104:107], v216
	ds_read_b128 v[108:111], v216 offset:8192
	v_exp_f32_e32 v112, v152
	v_exp_f32_e32 v113, v153
	v_exp_f32_e32 v114, v134
	v_exp_f32_e32 v115, v135
	s_waitcnt lgkmcnt(0)
	v_mfma_f32_32x32x16_bf16 v[80:95], v[104:107], v[100:103], v[80:95]
	v_mfma_f32_32x32x16_bf16 v[64:79], v[108:111], v[100:103], v[64:79]
	ds_read_b128 v[100:103], v217
	ds_read_b128 v[104:107], v217 offset:8192
	v_exp_f32_e32 v108, v156
	v_exp_f32_e32 v109, v157
	v_exp_f32_e32 v110, v154
	v_exp_f32_e32 v111, v155
	s_waitcnt lgkmcnt(0)
	v_mfma_f32_32x32x16_bf16 v[80:95], v[100:103], v[96:99], v[80:95]
	v_mfma_f32_32x32x16_bf16 v[64:79], v[104:107], v[96:99], v[64:79]
	ds_read_b128 v[96:99], v219
	ds_read_b128 v[100:103], v219 offset:4096
	ds_read_b128 v[104:107], v164
	s_waitcnt lgkmcnt(0)
	v_mfma_f32_32x32x16_bf16 v[80:95], v[96:99], v[104:107], v[80:95]
	v_mfma_f32_32x32x16_bf16 v[64:79], v[100:103], v[104:107], v[64:79]
	ds_read_b128 v[96:99], v218
	ds_read_b128 v[100:103], v218 offset:4096
	ds_read_b128 v[104:107], v164 offset:1024
	s_waitcnt lgkmcnt(0)
	v_mfma_f32_32x32x16_bf16 v[80:95], v[96:99], v[104:107], v[80:95]
	v_mfma_f32_32x32x16_bf16 v[64:79], v[100:103], v[104:107], v[64:79]
	ds_read_b128 v[96:99], v220
	ds_read_b128 v[100:103], v220 offset:4096
	ds_read_b128 v[104:107], v164 offset:2048
	s_waitcnt lgkmcnt(0)
	v_mfma_f32_32x32x16_bf16 v[80:95], v[96:99], v[104:107], v[80:95]
	v_mfma_f32_32x32x16_bf16 v[64:79], v[100:103], v[104:107], v[64:79]
	ds_read_b128 v[96:99], v221
	ds_read_b128 v[100:103], v221 offset:4096
	ds_read_b128 v[104:107], v164 offset:3072
	s_waitcnt lgkmcnt(0)
	v_mfma_f32_32x32x16_bf16 v[80:95], v[96:99], v[104:107], v[80:95]
	v_add_f32_e32 v96, 0, v236
	v_add_f32_e32 v96, v238, v96
	v_add_f32_e32 v96, v234, v96
	v_add_f32_e32 v96, v237, v96
	v_add_f32_e32 v96, v233, v96
	v_add_f32_e32 v96, v235, v96
	v_add_f32_e32 v96, v231, v96
	v_add_f32_e32 v96, v232, v96
	v_add_f32_e32 v96, v228, v96
	v_add_f32_e32 v96, v230, v96
	v_add_f32_e32 v96, v227, v96
	v_add_f32_e32 v96, v229, v96
	v_mfma_f32_32x32x16_bf16 v[64:79], v[100:103], v[104:107], v[64:79]
	v_exp_f32_e32 v106, v158
	v_add_f32_e32 v96, v224, v96
	v_exp_f32_e32 v107, v159
	v_add_f32_e32 v96, v226, v96
	v_add_f32_e32 v96, v223, v96
	v_add_f32_e32 v96, v225, v96
	v_add_f32_e32 v96, v106, v96
	v_add_f32_e32 v96, v107, v96
	v_add_f32_e32 v96, v108, v96
	v_add_f32_e32 v96, v109, v96
	v_add_f32_e32 v96, v110, v96
	v_add_f32_e32 v96, v111, v96
	v_add_f32_e32 v96, v112, v96
	v_add_f32_e32 v96, v113, v96
	v_add_f32_e32 v96, v114, v96
	v_add_f32_e32 v96, v115, v96
	v_add_f32_e32 v96, v116, v96
	v_add_f32_e32 v96, v117, v96
	v_add_f32_e32 v96, v118, v96
	v_add_f32_e32 v96, v119, v96
	v_add_f32_e32 v96, v120, v96
	v_add_f32_e32 v104, v121, v96
	v_mov_b32_e32 v105, v104
	v_cvt_pk_bf16_f32 v96, v236, v238
	v_cvt_pk_bf16_f32 v97, v234, v237
	v_cvt_pk_bf16_f32 v98, v233, v235
	v_cvt_pk_bf16_f32 v99, v231, v232
	s_nop 1
	v_permlane32_swap_b32_e32 v104, v105
	v_permlane32_swap_b32_e32 v96, v98
	v_permlane32_swap_b32_e32 v97, v99
	v_cvt_pk_bf16_f32 v100, v228, v230
	v_cvt_pk_bf16_f32 v101, v227, v229
	v_cvt_pk_bf16_f32 v102, v224, v226
	v_cvt_pk_bf16_f32 v103, v223, v225
	v_cvt_pk_bf16_f32 v106, v106, v107
	v_cvt_pk_bf16_f32 v107, v108, v109
	v_cvt_pk_bf16_f32 v108, v110, v111
	v_cvt_pk_bf16_f32 v109, v112, v113
	v_cvt_pk_bf16_f32 v110, v114, v115
	v_cvt_pk_bf16_f32 v111, v116, v117
	v_cvt_pk_bf16_f32 v112, v118, v119
	v_cvt_pk_bf16_f32 v113, v120, v121
	s_nop 0
	v_permlane32_swap_b32_e32 v100, v102
	v_permlane32_swap_b32_e32 v101, v103
	v_permlane32_swap_b32_e32 v106, v108
	v_permlane32_swap_b32_e32 v107, v109
	v_permlane32_swap_b32_e32 v110, v112
	v_permlane32_swap_b32_e32 v111, v113
	s_cmp_lg_u32 0, -1
	s_cselect_b32 s8, 0, 0
	s_add_i32 s8, s8, 0x8000
	v_add_u32_e32 v130, s8, v165
	ds_read_b64_tr_b16 v[114:115], v130 offset:0
	ds_read_b64_tr_b16 v[116:117], v130 offset:0x800
	ds_read_b64_tr_b16 v[118:119], v130 offset:0x1000
	ds_read_b64_tr_b16 v[120:121], v130 offset:0x1800
	ds_read_b64_tr_b16 v[122:123], v130 offset:0x2000
	ds_read_b64_tr_b16 v[124:125], v130 offset:0x2800
	ds_read_b64_tr_b16 v[126:127], v130 offset:0x3000
	ds_read_b64_tr_b16 v[128:129], v130 offset:0x3800
	s_nop 0
	s_waitcnt lgkmcnt(6)
	s_nop 0
	v_mfma_f32_32x32x16_bf16 v[0:15], v[96:99], v[114:117], v[0:15]
	s_waitcnt lgkmcnt(4)
	s_nop 0
	v_mfma_f32_32x32x16_bf16 v[0:15], v[100:103], v[118:121], v[0:15]
	s_waitcnt lgkmcnt(2)
	s_nop 0
	v_mfma_f32_32x32x16_bf16 v[0:15], v[106:109], v[122:125], v[0:15]
	s_waitcnt lgkmcnt(0)
	ds_read_b64_tr_b16 v[114:115], v130 offset:0x200
	ds_read_b64_tr_b16 v[116:117], v130 offset:0xa00
	ds_read_b64_tr_b16 v[118:119], v130 offset:0x1200
	ds_read_b64_tr_b16 v[120:121], v130 offset:0x1a00
	s_nop 0
	v_mfma_f32_32x32x16_bf16 v[0:15], v[110:113], v[126:129], v[0:15]
	ds_read_b64_tr_b16 v[122:123], v130 offset:0x2200
	ds_read_b64_tr_b16 v[124:125], v130 offset:0x2a00
	ds_read_b64_tr_b16 v[126:127], v130 offset:0x3200
	ds_read_b64_tr_b16 v[128:129], v130 offset:0x3a00
	s_waitcnt lgkmcnt(6)
	s_nop 0
	v_mfma_f32_32x32x16_bf16 v[48:63], v[96:99], v[114:117], v[48:63]
	s_waitcnt lgkmcnt(4)
	s_nop 0
	v_mfma_f32_32x32x16_bf16 v[48:63], v[100:103], v[118:121], v[48:63]
	s_waitcnt lgkmcnt(2)
	s_nop 0
	v_mfma_f32_32x32x16_bf16 v[48:63], v[106:109], v[122:125], v[48:63]
	s_waitcnt lgkmcnt(0)
	ds_read_b64_tr_b16 v[114:115], v130 offset:0x400
	ds_read_b64_tr_b16 v[116:117], v130 offset:0xc00
	ds_read_b64_tr_b16 v[118:119], v130 offset:0x1400
	ds_read_b64_tr_b16 v[120:121], v130 offset:0x1c00
	s_nop 0
	v_mfma_f32_32x32x16_bf16 v[48:63], v[110:113], v[126:129], v[48:63]
	ds_read_b64_tr_b16 v[122:123], v130 offset:0x2400
	ds_read_b64_tr_b16 v[124:125], v130 offset:0x2c00
	ds_read_b64_tr_b16 v[126:127], v130 offset:0x3400
	ds_read_b64_tr_b16 v[128:129], v130 offset:0x3c00
	s_waitcnt lgkmcnt(6)
	s_nop 0
	v_mfma_f32_32x32x16_bf16 v[32:47], v[96:99], v[114:117], v[32:47]
	s_waitcnt lgkmcnt(4)
	s_nop 0
	v_mfma_f32_32x32x16_bf16 v[32:47], v[100:103], v[118:121], v[32:47]
	s_waitcnt lgkmcnt(2)
	s_nop 0
	v_mfma_f32_32x32x16_bf16 v[32:47], v[106:109], v[122:125], v[32:47]
	s_waitcnt lgkmcnt(0)
	ds_read_b64_tr_b16 v[114:115], v130 offset:0x600
	ds_read_b64_tr_b16 v[116:117], v130 offset:0xe00
	ds_read_b64_tr_b16 v[118:119], v130 offset:0x1600
	ds_read_b64_tr_b16 v[120:121], v130 offset:0x1e00
	s_nop 0
	v_mfma_f32_32x32x16_bf16 v[32:47], v[110:113], v[126:129], v[32:47]
	ds_read_b64_tr_b16 v[122:123], v130 offset:0x2600
	ds_read_b64_tr_b16 v[124:125], v130 offset:0x2e00
	ds_read_b64_tr_b16 v[126:127], v130 offset:0x3600
	ds_read_b64_tr_b16 v[128:129], v130 offset:0x3e00
	s_waitcnt lgkmcnt(6)
	s_nop 0
	v_mfma_f32_32x32x16_bf16 v[16:31], v[96:99], v[114:117], v[16:31]
	s_waitcnt lgkmcnt(4)
	s_nop 0
	v_mfma_f32_32x32x16_bf16 v[16:31], v[100:103], v[118:121], v[16:31]
	s_waitcnt lgkmcnt(2)
	s_nop 0
	v_mfma_f32_32x32x16_bf16 v[16:31], v[106:109], v[122:125], v[16:31]
	s_waitcnt lgkmcnt(0)
	v_max_f32_e32 v96, v81, v81
	v_max_f32_e32 v97, v80, v80
	v_max_f32_e32 v96, v97, v96
	v_max3_f32 v96, v96, v82, v83
	v_max3_f32 v96, v96, v84, v85
	v_max3_f32 v96, v96, v86, v87
	v_max3_f32 v96, v96, v88, v89
	v_max3_f32 v96, v96, v90, v91
	v_max3_f32 v96, v96, v92, v93
	v_max3_f32 v96, v96, v94, v95
	v_max3_f32 v96, v96, v64, v65
	v_max3_f32 v96, v96, v66, v67
	v_max3_f32 v96, v96, v68, v69
	v_max3_f32 v96, v96, v70, v71
	v_max3_f32 v96, v96, v72, v73
	v_max3_f32 v96, v96, v74, v75
	v_max3_f32 v96, v96, v76, v77
	v_max3_f32 v96, v96, v78, v79
	v_mov_b32_e32 v97, v96
	s_nop 1
	v_permlane32_swap_b32_e32 v96, v97
	v_max_f32_e32 v97, v97, v97
	v_max_f32_e32 v96, v96, v96
	v_max_f32_e32 v96, v96, v97
	v_sub_f32_e32 v97, v96, v222
	v_cmp_ge_f32_e32 vcc, s97, v97
	v_max_f32_e32 v97, v222, v222
	v_max_f32_e32 v97, v97, v96
	v_mfma_f32_32x32x16_bf16 v[16:31], v[110:113], v[126:129], v[16:31]
	v_sub_f32_e32 v96, v222, v97
	v_mul_f32_e32 v96, 0x3f800000, v96
	v_exp_f32_e32 v96, v96
	s_cmp_eq_u64 vcc, exec
	s_cselect_b64 s[42:43], -1, 0
	v_cndmask_b32_e64 v96, v96, 1.0, s[42:43]
	v_cmp_gt_f32_e32 vcc, 1.0, v96
	s_cbranch_vccz .LBB0_56
	s_and_saveexec_b64 s[12:13], s[40:41]
	s_mov_b32 s77, 0x8000
	ds_write_b32 v162, v96 offset:128
	s_or_b64 exec, exec, s[12:13]
	s_waitcnt lgkmcnt(0)
	v_add_u32_e32 v102, s37, v184
	ds_read_b128 v[98:101], v102 offset:224
	ds_read_b128 v[106:109], v102 offset:192
	ds_read_b128 v[110:113], v102 offset:160
	ds_read_b128 v[114:117], v102 offset:128
	s_waitcnt lgkmcnt(0)
	v_pk_mul_f32 v[12:13], v[12:13], v[98:99]
	v_pk_mul_f32 v[8:9], v[8:9], v[106:107]
	v_pk_mul_f32 v[4:5], v[4:5], v[110:111]
	v_pk_mul_f32 v[14:15], v[14:15], v[100:101]
	v_pk_mul_f32 v[10:11], v[10:11], v[108:109]
	v_pk_mul_f32 v[6:7], v[6:7], v[112:113]
	v_pk_mul_f32 v[2:3], v[2:3], v[116:117]
	v_pk_mul_f32 v[0:1], v[0:1], v[114:115]
	v_pk_mul_f32 v[60:61], v[60:61], v[98:99]
	v_pk_mul_f32 v[56:57], v[56:57], v[106:107]
	v_pk_mul_f32 v[52:53], v[52:53], v[110:111]
	v_pk_mul_f32 v[62:63], v[62:63], v[100:101]
	v_pk_mul_f32 v[58:59], v[58:59], v[108:109]
	v_pk_mul_f32 v[54:55], v[54:55], v[112:113]
	v_pk_mul_f32 v[50:51], v[50:51], v[116:117]
	v_pk_mul_f32 v[48:49], v[48:49], v[114:115]
	v_pk_mul_f32 v[44:45], v[44:45], v[98:99]
	v_pk_mul_f32 v[40:41], v[40:41], v[106:107]
	v_pk_mul_f32 v[36:37], v[36:37], v[110:111]
	v_pk_mul_f32 v[46:47], v[46:47], v[100:101]
	v_pk_mul_f32 v[42:43], v[42:43], v[108:109]
	v_pk_mul_f32 v[38:39], v[38:39], v[112:113]
	v_pk_mul_f32 v[34:35], v[34:35], v[116:117]
	v_pk_mul_f32 v[32:33], v[32:33], v[114:115]
	v_pk_mul_f32 v[28:29], v[28:29], v[98:99]
	v_pk_mul_f32 v[24:25], v[24:25], v[106:107]
	v_pk_mul_f32 v[20:21], v[20:21], v[110:111]
	v_pk_mul_f32 v[30:31], v[30:31], v[100:101]
	v_pk_mul_f32 v[26:27], v[26:27], v[108:109]
	v_pk_mul_f32 v[22:23], v[22:23], v[112:113]
	v_pk_mul_f32 v[18:19], v[18:19], v[116:117]
	v_pk_mul_f32 v[16:17], v[16:17], v[114:115]
	s_branch .LBB0_57

.LBB0_57:
	v_cndmask_b32_e64 v97, v97, v222, s[42:43]
	v_mul_f32_e32 v97, 0xbf800000, v97
	v_fmamk_f32 v80, v80, 0x3f800000, v97
	v_fmamk_f32 v81, v81, 0x3f800000, v97
	v_fmamk_f32 v82, v82, 0x3f800000, v97
	v_fmamk_f32 v83, v83, 0x3f800000, v97
	v_fmamk_f32 v84, v84, 0x3f800000, v97
	v_fmamk_f32 v85, v85, 0x3f800000, v97
	v_fmamk_f32 v86, v86, 0x3f800000, v97
	v_fmamk_f32 v87, v87, 0x3f800000, v97
	v_fmamk_f32 v88, v88, 0x3f800000, v97
	v_fmamk_f32 v89, v89, 0x3f800000, v97
	v_fmamk_f32 v90, v90, 0x3f800000, v97
	v_fmamk_f32 v91, v91, 0x3f800000, v97
	v_fmamk_f32 v92, v92, 0x3f800000, v97
	v_fmamk_f32 v93, v93, 0x3f800000, v97
	v_fmamk_f32 v94, v94, 0x3f800000, v97
	v_fmamk_f32 v95, v95, 0x3f800000, v97
	v_fmamk_f32 v64, v64, 0x3f800000, v97
	v_fmamk_f32 v65, v65, 0x3f800000, v97
	v_fmamk_f32 v66, v66, 0x3f800000, v97
	v_fmamk_f32 v67, v67, 0x3f800000, v97
	v_fmamk_f32 v68, v68, 0x3f800000, v97
	v_fmamk_f32 v69, v69, 0x3f800000, v97
	v_fmamk_f32 v70, v70, 0x3f800000, v97
	v_fmamk_f32 v71, v71, 0x3f800000, v97
	v_fmamk_f32 v72, v72, 0x3f800000, v97
	v_fmamk_f32 v73, v73, 0x3f800000, v97
	v_fmamk_f32 v74, v74, 0x3f800000, v97
	v_fmamk_f32 v75, v75, 0x3f800000, v97
	v_fmamk_f32 v76, v76, 0x3f800000, v97
	v_fmamk_f32 v77, v77, 0x3f800000, v97
	v_fmamk_f32 v78, v78, 0x3f800000, v97
	v_fmac_f32_e32 v97, 0x3f800000, v79
	v_exp_f32_e32 v79, v80
	v_exp_f32_e32 v80, v81
	v_exp_f32_e32 v81, v82
	v_exp_f32_e32 v82, v83
	v_exp_f32_e32 v83, v84
	v_exp_f32_e32 v84, v85
	v_exp_f32_e32 v85, v86
	v_exp_f32_e32 v86, v87
	v_exp_f32_e32 v87, v88
	v_exp_f32_e32 v88, v89
	v_exp_f32_e32 v89, v90
	v_exp_f32_e32 v90, v91
	v_exp_f32_e32 v91, v92
	v_exp_f32_e32 v92, v93
	v_exp_f32_e32 v93, v94
	v_exp_f32_e32 v94, v95
	v_exp_f32_e32 v95, v64
	v_add_f32_e32 v64, 0, v79
	v_add_f32_e32 v64, v80, v64
	v_add_f32_e32 v64, v81, v64
	v_add_f32_e32 v64, v82, v64
	v_add_f32_e32 v64, v83, v64
	v_add_f32_e32 v64, v84, v64
	v_add_f32_e32 v64, v85, v64
	v_add_f32_e32 v64, v86, v64
	v_add_f32_e32 v64, v87, v64
	v_add_f32_e32 v64, v88, v64
	v_add_f32_e32 v64, v89, v64
	v_add_f32_e32 v64, v90, v64
	v_add_f32_e32 v64, v91, v64
	v_exp_f32_e32 v98, v65
	v_add_f32_e32 v64, v92, v64
	v_exp_f32_e32 v99, v66
	v_add_f32_e32 v64, v93, v64
	v_exp_f32_e32 v100, v67
	v_add_f32_e32 v64, v94, v64
	v_exp_f32_e32 v101, v68
	v_add_f32_e32 v64, v95, v64
	v_exp_f32_e32 v102, v69
	v_add_f32_e32 v64, v98, v64
	v_exp_f32_e32 v103, v70
	v_add_f32_e32 v64, v99, v64
	v_exp_f32_e32 v106, v71
	v_add_f32_e32 v64, v100, v64
	v_exp_f32_e32 v107, v72
	v_add_f32_e32 v64, v101, v64
	v_exp_f32_e32 v108, v73
	v_add_f32_e32 v64, v102, v64
	v_exp_f32_e32 v109, v74
	v_add_f32_e32 v64, v103, v64
	v_exp_f32_e32 v110, v75
	v_add_f32_e32 v64, v106, v64
	v_exp_f32_e32 v111, v76
	v_add_f32_e32 v64, v107, v64
	v_exp_f32_e32 v112, v77
	v_add_f32_e32 v64, v108, v64
	v_exp_f32_e32 v113, v78
	v_add_f32_e32 v64, v109, v64
	v_exp_f32_e32 v97, v97
	v_add_f32_e32 v64, v110, v64
	v_add_f32_e32 v64, v111, v64
	v_add_f32_e32 v64, v112, v64
	v_add_f32_e32 v64, v113, v64
	s_waitcnt vmcnt(0) lgkmcnt(0)
	s_barrier
	v_add_f32_e32 v64, v97, v64
	v_mov_b32_e32 v65, v64
	s_nop 1
	v_permlane32_swap_b32_e32 v64, v65
	v_cvt_pk_bf16_f32 v66, v79, v80
	v_cvt_pk_bf16_f32 v67, v81, v82
	v_cvt_pk_bf16_f32 v68, v83, v84
	v_cvt_pk_bf16_f32 v69, v85, v86
	v_cvt_pk_bf16_f32 v70, v87, v88
	v_cvt_pk_bf16_f32 v71, v89, v90
	v_cvt_pk_bf16_f32 v72, v91, v92
	v_cvt_pk_bf16_f32 v73, v93, v94
	v_cvt_pk_bf16_f32 v74, v95, v98
	v_cvt_pk_bf16_f32 v75, v99, v100
	v_cvt_pk_bf16_f32 v76, v101, v102
	v_cvt_pk_bf16_f32 v77, v103, v106
	v_cvt_pk_bf16_f32 v78, v107, v108
	v_cvt_pk_bf16_f32 v79, v109, v110
	v_cvt_pk_bf16_f32 v80, v111, v112
	v_cvt_pk_bf16_f32 v81, v113, v97
	s_nop 0
	v_permlane32_swap_b32_e32 v66, v68
	v_permlane32_swap_b32_e32 v67, v69
	v_permlane32_swap_b32_e32 v70, v72
	v_permlane32_swap_b32_e32 v71, v73
	v_permlane32_swap_b32_e32 v74, v76
	v_permlane32_swap_b32_e32 v75, v77
	v_permlane32_swap_b32_e32 v78, v80
	v_permlane32_swap_b32_e32 v79, v81
	ds_read_b64_tr_b16 v[82:83], v161 offset:0
	ds_read_b64_tr_b16 v[84:85], v161 offset:0x800
	ds_read_b64_tr_b16 v[86:87], v161 offset:0x1000
	ds_read_b64_tr_b16 v[88:89], v161 offset:0x1800
	ds_read_b64_tr_b16 v[90:91], v161 offset:0x2000
	ds_read_b64_tr_b16 v[92:93], v161 offset:0x2800
	ds_read_b64_tr_b16 v[98:99], v161 offset:0x3000
	ds_read_b64_tr_b16 v[100:101], v161 offset:0x3800
	s_nop 0
	s_waitcnt lgkmcnt(6)
	s_nop 0
	v_mfma_f32_32x32x16_bf16 v[0:15], v[66:69], v[82:85], v[0:15]
	s_waitcnt lgkmcnt(4)
	s_nop 0
	v_mfma_f32_32x32x16_bf16 v[0:15], v[70:73], v[86:89], v[0:15]
	s_waitcnt lgkmcnt(2)
	s_nop 0
	v_mfma_f32_32x32x16_bf16 v[0:15], v[74:77], v[90:93], v[0:15]
	s_waitcnt lgkmcnt(0)
	ds_read_b64_tr_b16 v[82:83], v161 offset:0x200
	ds_read_b64_tr_b16 v[84:85], v161 offset:0xa00
	ds_read_b64_tr_b16 v[86:87], v161 offset:0x1200
	ds_read_b64_tr_b16 v[88:89], v161 offset:0x1a00
	s_nop 0
	v_mfma_f32_32x32x16_bf16 v[0:15], v[78:81], v[98:101], v[0:15]
	ds_read_b64_tr_b16 v[90:91], v161 offset:0x2200
	ds_read_b64_tr_b16 v[92:93], v161 offset:0x2a00
	ds_read_b64_tr_b16 v[98:99], v161 offset:0x3200
	ds_read_b64_tr_b16 v[100:101], v161 offset:0x3a00
	s_waitcnt lgkmcnt(6)
	s_nop 0
	v_mfma_f32_32x32x16_bf16 v[48:63], v[66:69], v[82:85], v[48:63]
	s_waitcnt lgkmcnt(4)
	s_nop 0
	v_mfma_f32_32x32x16_bf16 v[48:63], v[70:73], v[86:89], v[48:63]
	s_waitcnt lgkmcnt(2)
	s_nop 0
	v_mfma_f32_32x32x16_bf16 v[48:63], v[74:77], v[90:93], v[48:63]
	s_waitcnt lgkmcnt(0)
	ds_read_b64_tr_b16 v[82:83], v161 offset:0x400
	ds_read_b64_tr_b16 v[84:85], v161 offset:0xc00
	ds_read_b64_tr_b16 v[86:87], v161 offset:0x1400
	ds_read_b64_tr_b16 v[88:89], v161 offset:0x1c00
	s_nop 0
	v_mfma_f32_32x32x16_bf16 v[48:63], v[78:81], v[98:101], v[48:63]
	ds_read_b64_tr_b16 v[90:91], v161 offset:0x2400
	ds_read_b64_tr_b16 v[92:93], v161 offset:0x2c00
	ds_read_b64_tr_b16 v[98:99], v161 offset:0x3400
	ds_read_b64_tr_b16 v[100:101], v161 offset:0x3c00
	s_waitcnt lgkmcnt(6)
	s_nop 0
	v_mfma_f32_32x32x16_bf16 v[32:47], v[66:69], v[82:85], v[32:47]
	s_waitcnt lgkmcnt(4)
	s_nop 0
	v_mfma_f32_32x32x16_bf16 v[32:47], v[70:73], v[86:89], v[32:47]
	s_waitcnt lgkmcnt(2)
	s_nop 0
	v_mfma_f32_32x32x16_bf16 v[32:47], v[74:77], v[90:93], v[32:47]
	s_waitcnt lgkmcnt(0)
	ds_read_b64_tr_b16 v[82:83], v161 offset:0x600
	ds_read_b64_tr_b16 v[84:85], v161 offset:0xe00
	ds_read_b64_tr_b16 v[86:87], v161 offset:0x1600
	ds_read_b64_tr_b16 v[88:89], v161 offset:0x1e00
	s_nop 0
	v_mfma_f32_32x32x16_bf16 v[32:47], v[78:81], v[98:101], v[32:47]
	ds_read_b64_tr_b16 v[90:91], v161 offset:0x2600
	ds_read_b64_tr_b16 v[92:93], v161 offset:0x2e00
	ds_read_b64_tr_b16 v[98:99], v161 offset:0x3600
	ds_read_b64_tr_b16 v[100:101], v161 offset:0x3e00
	s_waitcnt lgkmcnt(6)
	s_nop 0
	v_mfma_f32_32x32x16_bf16 v[16:31], v[66:69], v[82:85], v[16:31]
	s_waitcnt lgkmcnt(4)
	s_nop 0
	v_mfma_f32_32x32x16_bf16 v[16:31], v[70:73], v[86:89], v[16:31]
	s_waitcnt lgkmcnt(2)
	s_nop 0
	v_mfma_f32_32x32x16_bf16 v[16:31], v[74:77], v[90:93], v[16:31]
	s_waitcnt lgkmcnt(0)
	s_nop 0
	v_mfma_f32_32x32x16_bf16 v[16:31], v[78:81], v[98:101], v[16:31]
	s_waitcnt vmcnt(0) lgkmcnt(0)
	s_barrier
	s_and_saveexec_b64 s[12:13], s[40:41]
	s_cbranch_execz .LBB0_40
	v_add_f32_e32 v66, v104, v105
	v_fmac_f32_e32 v66, v163, v144
	v_add_f32_e32 v64, v64, v65
	v_fmac_f32_e32 v64, v66, v96
	ds_write_b32 v162, v64
	s_branch .LBB0_40

.LBB0_104:
	s_lshl_b32 s8, s51, 8
	v_mov_b32_e32 v128, v214
	s_add_i32 s8, s8, s38
	s_nop 0
	v_add_u32_e32 v225, s8, v128
	v_mad_i64_i32 v[128:129], s[12:13], v225, 48, s[44:45]
	global_load_dwordx4 v[226:229], v[128:129], off
	global_load_dwordx4 v[230:233], v[128:129], off offset:16
	v_add_u32_e32 v224, 16, v225
	v_mad_i64_i32 v[128:129], s[12:13], v224, 48, s[44:45]
	global_load_dwordx4 v[180:183], v[128:129], off
	global_load_dwordx4 v[176:179], v[128:129], off offset:16
	v_add_u32_e32 v223, 32, v225
	v_mad_i64_i32 v[128:129], s[12:13], v223, 48, s[44:45]
	global_load_dwordx4 v[172:175], v[128:129], off
	global_load_dwordx4 v[168:171], v[128:129], off offset:16
	v_add_u32_e32 v222, 48, v225
	v_mad_i64_i32 v[128:129], s[12:13], v222, 48, s[44:45]
	global_load_dwordx4 v[164:167], v[128:129], off
	global_load_dwordx4 v[160:163], v[128:129], off offset:16
	v_add_u32_e32 v221, 0x80, v225
	v_mad_i64_i32 v[128:129], s[12:13], v221, 48, s[44:45]
	global_load_dwordx4 v[156:159], v[128:129], off
	global_load_dwordx4 v[152:155], v[128:129], off offset:16
	v_add_u32_e32 v220, 0x90, v225
	v_mad_i64_i32 v[128:129], s[12:13], v220, 48, s[44:45]
	global_load_dwordx4 v[148:151], v[128:129], off
	global_load_dwordx4 v[144:147], v[128:129], off offset:16
	v_add_u32_e32 v219, 0xa0, v225
	v_mad_i64_i32 v[128:129], s[12:13], v219, 48, s[44:45]
	global_load_dwordx4 v[140:143], v[128:129], off
	global_load_dwordx4 v[136:139], v[128:129], off offset:16
	v_add_u32_e32 v218, 0xb0, v225
	v_mad_i64_i32 v[128:129], s[12:13], v218, 48, s[44:45]
	global_load_dwordx4 v[132:135], v[128:129], off
	s_nop 0
	global_load_dwordx4 v[128:131], v[128:129], off offset:16
	s_waitcnt vmcnt(0)
	v_mov_b32_e32 v186, v226
	v_mov_b32_e32 v187, v230
	v_mov_b32_e32 v230, v227
	v_mov_b32_e32 v188, v228
	v_mov_b32_e32 v189, v232
	v_mov_b32_e32 v232, v229
	v_pk_add_f32 v[186:187], v[186:187], v[230:231]
	v_pk_add_f32 v[188:189], v[188:189], v[232:233]
	s_nop 0
	v_pk_add_f32 v[186:187], v[186:187], v[188:189]
	s_nop 0
	v_add_f32_e32 v186, v186, v187
	v_fmamk_f32 v186, v186, 0x3b000000, v204
	v_cmp_gt_f32_e32 vcc, s94, v186
	v_mul_f32_e32 v187, 0x4f800000, v186
	s_nop 0
	v_cndmask_b32_e32 v186, v186, v187, vcc
	v_sqrt_f32_e32 v187, v186
	s_nop 0
	v_add_u32_e32 v188, -1, v187
	v_fma_f32 v189, -v188, v187, v186
	v_cmp_ge_f32_e64 s[42:43], 0, v189
	v_add_u32_e32 v189, 1, v187
	s_nop 0
	v_cndmask_b32_e64 v188, v187, v188, s[42:43]
	v_fma_f32 v187, -v189, v187, v186
	v_cmp_lt_f32_e64 s[42:43], 0, v187
	s_nop 1
	v_cndmask_b32_e64 v187, v188, v189, s[42:43]
	v_mul_f32_e32 v188, 0x37800000, v187
	v_cndmask_b32_e32 v187, v187, v188, vcc
	v_cmp_class_f32_e32 vcc, v186, v205
	s_nop 1
	v_cndmask_b32_e32 v186, v187, v186, vcc
	v_div_scale_f32 v187, s[12:13], v186, v186, 1.0
	v_rcp_f32_e32 v188, v187
	s_nop 0
	v_fma_f32 v189, -v187, v188, 1.0
	v_fmac_f32_e32 v188, v189, v188
	v_div_scale_f32 v189, vcc, 1.0, v186, 1.0
	v_mul_f32_e32 v202, v189, v188
	v_fma_f32 v226, -v187, v202, v189
	v_fmac_f32_e32 v202, v226, v188
	v_fma_f32 v187, -v187, v202, v189
	v_div_fmas_f32 v187, v187, v188, v202
	v_div_fixup_f32 v202, v187, v186, 1.0
	v_mul_f32_e32 v202, 0x3dd53b94, v202
	v_mov_b32_e32 v186, v180
	v_mov_b32_e32 v187, v176
	v_mov_b32_e32 v176, v181
	v_mov_b32_e32 v180, v182
	v_mov_b32_e32 v181, v178
	v_mov_b32_e32 v178, v183
	v_pk_add_f32 v[176:177], v[186:187], v[176:177]
	v_pk_add_f32 v[178:179], v[180:181], v[178:179]
	s_nop 0
	v_pk_add_f32 v[176:177], v[176:177], v[178:179]
	s_nop 0
	v_add_f32_e32 v176, v176, v177
	v_fmamk_f32 v176, v176, 0x3b000000, v204
	v_cmp_gt_f32_e32 vcc, s94, v176
	v_mul_f32_e32 v177, 0x4f800000, v176
	s_nop 0
	v_cndmask_b32_e32 v176, v176, v177, vcc
	v_sqrt_f32_e32 v177, v176
	s_nop 0
	v_add_u32_e32 v178, -1, v177
	v_fma_f32 v179, -v178, v177, v176
	v_cmp_ge_f32_e64 s[42:43], 0, v179
	v_add_u32_e32 v179, 1, v177
	s_nop 0
	v_cndmask_b32_e64 v178, v177, v178, s[42:43]
	v_fma_f32 v177, -v179, v177, v176
	v_cmp_lt_f32_e64 s[42:43], 0, v177
	s_nop 1
	v_cndmask_b32_e64 v177, v178, v179, s[42:43]
	v_mul_f32_e32 v178, 0x37800000, v177
	v_cndmask_b32_e32 v177, v177, v178, vcc
	v_cmp_class_f32_e32 vcc, v176, v205
	s_nop 1
	v_cndmask_b32_e32 v176, v177, v176, vcc
	v_div_scale_f32 v177, s[12:13], v176, v176, 1.0
	v_rcp_f32_e32 v178, v177
	s_nop 0
	v_fma_f32 v179, -v177, v178, 1.0
	v_fmac_f32_e32 v178, v179, v178
	v_div_scale_f32 v179, vcc, 1.0, v176, 1.0
	v_mul_f32_e32 v180, v179, v178
	v_fma_f32 v181, -v177, v180, v179
	v_fmac_f32_e32 v180, v181, v178
	v_fma_f32 v177, -v177, v180, v179
	v_div_fmas_f32 v177, v177, v178, v180
	v_mov_b32_e32 v178, v172
	v_mov_b32_e32 v179, v168
	v_mov_b32_e32 v168, v173
	v_mov_b32_e32 v172, v174
	v_mov_b32_e32 v173, v170
	v_mov_b32_e32 v170, v175
	v_pk_add_f32 v[168:169], v[178:179], v[168:169]
	v_pk_add_f32 v[170:171], v[172:173], v[170:171]
	v_div_fixup_f32 v176, v177, v176, 1.0
	v_mul_f32_e32 v176, 0x3dd53b94, v176
	v_pk_add_f32 v[168:169], v[168:169], v[170:171]
	s_nop 0
	v_add_f32_e32 v168, v168, v169
	v_fmamk_f32 v168, v168, 0x3b000000, v204
	v_cmp_gt_f32_e32 vcc, s94, v168
	v_mul_f32_e32 v169, 0x4f800000, v168
	s_nop 0
	v_cndmask_b32_e32 v168, v168, v169, vcc
	v_sqrt_f32_e32 v169, v168
	s_nop 0
	v_add_u32_e32 v170, -1, v169
	v_fma_f32 v171, -v170, v169, v168
	v_cmp_ge_f32_e64 s[42:43], 0, v171
	v_add_u32_e32 v171, 1, v169
	s_nop 0
	v_cndmask_b32_e64 v170, v169, v170, s[42:43]
	v_fma_f32 v169, -v171, v169, v168
	v_cmp_lt_f32_e64 s[42:43], 0, v169
	s_nop 1
	v_cndmask_b32_e64 v169, v170, v171, s[42:43]
	v_mul_f32_e32 v170, 0x37800000, v169
	v_cndmask_b32_e32 v169, v169, v170, vcc
	v_cmp_class_f32_e32 vcc, v168, v205
	s_nop 1
	v_cndmask_b32_e32 v168, v169, v168, vcc
	v_div_scale_f32 v169, s[12:13], v168, v168, 1.0
	v_rcp_f32_e32 v170, v169
	s_nop 0
	v_fma_f32 v171, -v169, v170, 1.0
	v_fmac_f32_e32 v170, v171, v170
	v_div_scale_f32 v171, vcc, 1.0, v168, 1.0
	v_mul_f32_e32 v172, v171, v170
	v_fma_f32 v173, -v169, v172, v171
	v_fmac_f32_e32 v172, v173, v170
	v_fma_f32 v169, -v169, v172, v171
	v_div_fmas_f32 v169, v169, v170, v172
	v_mov_b32_e32 v170, v164
	v_mov_b32_e32 v171, v160
	v_mov_b32_e32 v160, v165
	v_mov_b32_e32 v164, v166
	v_mov_b32_e32 v165, v162
	v_mov_b32_e32 v162, v167
	v_pk_add_f32 v[160:161], v[170:171], v[160:161]
	v_pk_add_f32 v[162:163], v[164:165], v[162:163]
	v_div_fixup_f32 v168, v169, v168, 1.0
	v_mul_f32_e32 v168, 0x3dd53b94, v168
	v_pk_add_f32 v[160:161], v[160:161], v[162:163]
	s_nop 0
	v_add_f32_e32 v160, v160, v161
	v_fmamk_f32 v160, v160, 0x3b000000, v204
	v_cmp_gt_f32_e32 vcc, s94, v160
	v_mul_f32_e32 v161, 0x4f800000, v160
	s_nop 0
	v_cndmask_b32_e32 v160, v160, v161, vcc
	v_sqrt_f32_e32 v161, v160
	s_nop 0
	v_add_u32_e32 v162, -1, v161
	v_fma_f32 v163, -v162, v161, v160
	v_cmp_ge_f32_e64 s[42:43], 0, v163
	v_add_u32_e32 v163, 1, v161
	s_nop 0
	v_cndmask_b32_e64 v162, v161, v162, s[42:43]
	v_fma_f32 v161, -v163, v161, v160
	v_cmp_lt_f32_e64 s[42:43], 0, v161
	s_nop 1
	v_cndmask_b32_e64 v161, v162, v163, s[42:43]
	v_mul_f32_e32 v162, 0x37800000, v161
	v_cndmask_b32_e32 v161, v161, v162, vcc
	v_cmp_class_f32_e32 vcc, v160, v205
	s_nop 1
	v_cndmask_b32_e32 v160, v161, v160, vcc
	v_div_scale_f32 v161, s[12:13], v160, v160, 1.0
	v_rcp_f32_e32 v162, v161
	s_nop 0
	v_fma_f32 v163, -v161, v162, 1.0
	v_fmac_f32_e32 v162, v163, v162
	v_div_scale_f32 v163, vcc, 1.0, v160, 1.0
	v_mul_f32_e32 v164, v163, v162
	v_fma_f32 v165, -v161, v164, v163
	v_fmac_f32_e32 v164, v165, v162
	v_fma_f32 v161, -v161, v164, v163
	v_div_fmas_f32 v161, v161, v162, v164
	v_mov_b32_e32 v162, v156
	v_mov_b32_e32 v163, v152
	v_mov_b32_e32 v152, v157
	v_mov_b32_e32 v156, v158
	v_mov_b32_e32 v157, v154
	v_mov_b32_e32 v154, v159
	v_pk_add_f32 v[152:153], v[162:163], v[152:153]
	v_pk_add_f32 v[154:155], v[156:157], v[154:155]
	v_div_fixup_f32 v160, v161, v160, 1.0
	v_mul_f32_e32 v160, 0x3dd53b94, v160
	v_pk_add_f32 v[152:153], v[152:153], v[154:155]
	s_nop 0
	v_add_f32_e32 v152, v152, v153
	v_fmamk_f32 v152, v152, 0x3b000000, v204
	v_cmp_gt_f32_e32 vcc, s94, v152
	v_mul_f32_e32 v153, 0x4f800000, v152
	s_nop 0
	v_cndmask_b32_e32 v152, v152, v153, vcc
	v_sqrt_f32_e32 v153, v152
	s_nop 0
	v_add_u32_e32 v154, -1, v153
	v_fma_f32 v155, -v154, v153, v152
	v_cmp_ge_f32_e64 s[42:43], 0, v155
	v_add_u32_e32 v155, 1, v153
	s_nop 0
	v_cndmask_b32_e64 v154, v153, v154, s[42:43]
	v_fma_f32 v153, -v155, v153, v152
	v_cmp_lt_f32_e64 s[42:43], 0, v153
	s_nop 1
	v_cndmask_b32_e64 v153, v154, v155, s[42:43]
	v_mul_f32_e32 v154, 0x37800000, v153
	v_cndmask_b32_e32 v153, v153, v154, vcc
	v_cmp_class_f32_e32 vcc, v152, v205
	s_nop 1
	v_cndmask_b32_e32 v152, v153, v152, vcc
	v_div_scale_f32 v153, s[12:13], v152, v152, 1.0
	v_rcp_f32_e32 v154, v153
	s_nop 0
	v_fma_f32 v155, -v153, v154, 1.0
	v_fmac_f32_e32 v154, v155, v154
	v_div_scale_f32 v155, vcc, 1.0, v152, 1.0
	v_mul_f32_e32 v156, v155, v154
	v_fma_f32 v157, -v153, v156, v155
	v_fmac_f32_e32 v156, v157, v154
	v_fma_f32 v153, -v153, v156, v155
	v_div_fmas_f32 v153, v153, v154, v156
	v_mov_b32_e32 v154, v148
	v_mov_b32_e32 v155, v144
	v_mov_b32_e32 v144, v149
	v_mov_b32_e32 v148, v150
	v_mov_b32_e32 v149, v146
	v_mov_b32_e32 v146, v151
	v_pk_add_f32 v[144:145], v[154:155], v[144:145]
	v_pk_add_f32 v[146:147], v[148:149], v[146:147]
	v_div_fixup_f32 v152, v153, v152, 1.0
	v_mul_f32_e32 v152, 0x3dd53b94, v152
	v_pk_add_f32 v[144:145], v[144:145], v[146:147]
	s_nop 0
	v_add_f32_e32 v144, v144, v145
	v_fmamk_f32 v144, v144, 0x3b000000, v204
	v_cmp_gt_f32_e32 vcc, s94, v144
	v_mul_f32_e32 v145, 0x4f800000, v144
	s_nop 0
	v_cndmask_b32_e32 v144, v144, v145, vcc
	v_sqrt_f32_e32 v145, v144
	s_nop 0
	v_add_u32_e32 v146, -1, v145
	v_fma_f32 v147, -v146, v145, v144
	v_cmp_ge_f32_e64 s[42:43], 0, v147
	v_add_u32_e32 v147, 1, v145
	s_nop 0
	v_cndmask_b32_e64 v146, v145, v146, s[42:43]
	v_fma_f32 v145, -v147, v145, v144
	v_cmp_lt_f32_e64 s[42:43], 0, v145
	s_nop 1
	v_cndmask_b32_e64 v145, v146, v147, s[42:43]
	v_mul_f32_e32 v146, 0x37800000, v145
	v_cndmask_b32_e32 v145, v145, v146, vcc
	v_cmp_class_f32_e32 vcc, v144, v205
	s_nop 1
	v_cndmask_b32_e32 v144, v145, v144, vcc
	v_div_scale_f32 v145, s[12:13], v144, v144, 1.0
	v_rcp_f32_e32 v146, v145
	s_nop 0
	v_fma_f32 v147, -v145, v146, 1.0
	v_fmac_f32_e32 v146, v147, v146
	v_div_scale_f32 v147, vcc, 1.0, v144, 1.0
	v_mul_f32_e32 v148, v147, v146
	v_fma_f32 v149, -v145, v148, v147
	v_fmac_f32_e32 v148, v149, v146
	v_fma_f32 v145, -v145, v148, v147
	v_div_fmas_f32 v145, v145, v146, v148
	v_mov_b32_e32 v146, v140
	v_mov_b32_e32 v147, v136
	v_mov_b32_e32 v136, v141
	v_mov_b32_e32 v140, v142
	v_mov_b32_e32 v141, v138
	v_mov_b32_e32 v138, v143
	v_pk_add_f32 v[136:137], v[146:147], v[136:137]
	v_pk_add_f32 v[138:139], v[140:141], v[138:139]
	v_div_fixup_f32 v144, v145, v144, 1.0
	v_mul_f32_e32 v144, 0x3dd53b94, v144
	v_pk_add_f32 v[136:137], v[136:137], v[138:139]
	s_nop 0
	v_add_f32_e32 v136, v136, v137
	v_fmamk_f32 v136, v136, 0x3b000000, v204
	v_cmp_gt_f32_e32 vcc, s94, v136
	v_mul_f32_e32 v137, 0x4f800000, v136
	s_nop 0
	v_cndmask_b32_e32 v136, v136, v137, vcc
	v_sqrt_f32_e32 v137, v136
	s_nop 0
	v_add_u32_e32 v138, -1, v137
	v_fma_f32 v139, -v138, v137, v136
	v_cmp_ge_f32_e64 s[42:43], 0, v139
	v_add_u32_e32 v139, 1, v137
	s_nop 0
	v_cndmask_b32_e64 v138, v137, v138, s[42:43]
	v_fma_f32 v137, -v139, v137, v136
	v_cmp_lt_f32_e64 s[42:43], 0, v137
	s_nop 1
	v_cndmask_b32_e64 v137, v138, v139, s[42:43]
	v_mul_f32_e32 v138, 0x37800000, v137
	v_cndmask_b32_e32 v137, v137, v138, vcc
	v_cmp_class_f32_e32 vcc, v136, v205
	s_nop 1
	v_cndmask_b32_e32 v136, v137, v136, vcc
	v_div_scale_f32 v137, s[12:13], v136, v136, 1.0
	v_rcp_f32_e32 v138, v137
	s_nop 0
	v_fma_f32 v139, -v137, v138, 1.0
	v_fmac_f32_e32 v138, v139, v138
	v_div_scale_f32 v139, vcc, 1.0, v136, 1.0
	v_mul_f32_e32 v140, v139, v138
	v_fma_f32 v141, -v137, v140, v139
	v_fmac_f32_e32 v140, v141, v138
	v_fma_f32 v137, -v137, v140, v139
	v_div_fmas_f32 v137, v137, v138, v140
	v_mov_b32_e32 v138, v132
	v_mov_b32_e32 v139, v128
	v_mov_b32_e32 v128, v133
	v_mov_b32_e32 v132, v134
	v_mov_b32_e32 v133, v130
	v_mov_b32_e32 v130, v135
	v_pk_add_f32 v[128:129], v[138:139], v[128:129]
	v_pk_add_f32 v[130:131], v[132:133], v[130:131]
	v_div_fixup_f32 v136, v137, v136, 1.0
	v_mul_f32_e32 v136, 0x3dd53b94, v136
	v_pk_add_f32 v[128:129], v[128:129], v[130:131]
	s_nop 0
	v_add_f32_e32 v128, v128, v129
	v_fmamk_f32 v128, v128, 0x3b000000, v204
	v_cmp_gt_f32_e32 vcc, s94, v128
	v_mul_f32_e32 v129, 0x4f800000, v128
	s_nop 0
	v_cndmask_b32_e32 v128, v128, v129, vcc
	v_sqrt_f32_e32 v129, v128
	s_nop 0
	v_add_u32_e32 v130, -1, v129
	v_fma_f32 v131, -v130, v129, v128
	v_cmp_ge_f32_e64 s[42:43], 0, v131
	v_add_u32_e32 v131, 1, v129
	s_nop 0
	v_cndmask_b32_e64 v130, v129, v130, s[42:43]
	v_fma_f32 v129, -v131, v129, v128
	v_cmp_lt_f32_e64 s[42:43], 0, v129
	s_nop 1
	v_cndmask_b32_e64 v129, v130, v131, s[42:43]
	v_mul_f32_e32 v130, 0x37800000, v129
	v_cndmask_b32_e32 v129, v129, v130, vcc
	v_cmp_class_f32_e32 vcc, v128, v205
	s_nop 1
	v_cndmask_b32_e32 v128, v129, v128, vcc
	v_div_scale_f32 v129, s[12:13], v128, v128, 1.0
	v_rcp_f32_e32 v130, v129
	s_nop 0
	v_fma_f32 v131, -v129, v130, 1.0
	v_fmac_f32_e32 v130, v131, v130
	v_div_scale_f32 v131, vcc, 1.0, v128, 1.0
	v_mul_f32_e32 v132, v131, v130
	v_fma_f32 v133, -v129, v132, v131
	v_fmac_f32_e32 v132, v133, v130
	v_fma_f32 v129, -v129, v132, v131
	v_div_fmas_f32 v129, v129, v130, v132
	v_div_fixup_f32 v128, v129, v128, 1.0
	v_mul_f32_e32 v128, 0x3dd53b94, v128
	v_lshl_or_b32 v132, s50, 8, v216
	v_ashrrev_i32_e32 v133, 31, v132
	v_mov_b64_e32 v[130:131], s[14:15]
	s_movk_i32 s8, 0xc00
	v_mad_i64_i32 v[134:135], s[12:13], v225, s8, v[130:131]
	v_lshlrev_b64 v[132:133], 1, v[132:133]
	v_lshl_add_u64 v[134:135], v[134:135], 0, v[132:133]
	v_pk_mul_f32 v[126:127], v[126:127], v[202:203] op_sel_hi:[1,0]
	v_pk_mul_f32 v[124:125], v[124:125], v[202:203] op_sel_hi:[1,0]
	v_pk_mul_f32 v[138:139], v[122:123], v[202:203] op_sel_hi:[1,0]
	v_pk_mul_f32 v[122:123], v[120:121], v[202:203] op_sel_hi:[1,0]
	v_cvt_pk_bf16_f32 v120, v124, v125
	v_cvt_pk_bf16_f32 v121, v126, v127
	v_pk_mul_f32 v[118:119], v[118:119], v[202:203] op_sel_hi:[1,0]
	v_cvt_pk_bf16_f32 v122, v122, v123
	v_cvt_pk_bf16_f32 v123, v138, v139
	global_store_dwordx4 v[134:135], v[120:123], off
	v_pk_mul_f32 v[116:117], v[116:117], v[202:203] op_sel_hi:[1,0]
	s_nop 0
	v_pk_mul_f32 v[120:121], v[110:111], v[202:203] op_sel_hi:[1,0]
	v_pk_mul_f32 v[110:111], v[108:109], v[202:203] op_sel_hi:[1,0]
	v_cvt_pk_bf16_f32 v108, v116, v117
	v_cvt_pk_bf16_f32 v109, v118, v119
	s_nop 0
	v_cvt_pk_bf16_f32 v110, v110, v111
	v_cvt_pk_bf16_f32 v111, v120, v121
	global_store_dwordx4 v[134:135], v[108:111], off offset:256
	s_nop 1
	v_mad_i64_i32 v[108:109], s[12:13], v224, s8, v[130:131]
	v_lshl_add_u64 v[108:109], v[108:109], 0, v[132:133]
	v_pk_mul_f32 v[110:111], v[114:115], v[176:177] op_sel_hi:[1,0]
	v_pk_mul_f32 v[112:113], v[112:113], v[176:177] op_sel_hi:[1,0]
	v_pk_mul_f32 v[114:115], v[106:107], v[176:177] op_sel_hi:[1,0]
	v_pk_mul_f32 v[106:107], v[104:105], v[176:177] op_sel_hi:[1,0]
	v_cvt_pk_bf16_f32 v104, v112, v113
	v_cvt_pk_bf16_f32 v105, v110, v111
	v_pk_mul_f32 v[102:103], v[102:103], v[176:177] op_sel_hi:[1,0]
	v_cvt_pk_bf16_f32 v106, v106, v107
	v_cvt_pk_bf16_f32 v107, v114, v115
	global_store_dwordx4 v[108:109], v[104:107], off
	v_pk_mul_f32 v[100:101], v[100:101], v[176:177] op_sel_hi:[1,0]
	s_nop 0
	v_pk_mul_f32 v[104:105], v[94:95], v[176:177] op_sel_hi:[1,0]
	v_pk_mul_f32 v[94:95], v[92:93], v[176:177] op_sel_hi:[1,0]
	v_cvt_pk_bf16_f32 v92, v100, v101
	v_cvt_pk_bf16_f32 v93, v102, v103
	s_nop 0
	v_cvt_pk_bf16_f32 v94, v94, v95
	v_cvt_pk_bf16_f32 v95, v104, v105
	global_store_dwordx4 v[108:109], v[92:95], off offset:256
	s_nop 1
	v_mad_i64_i32 v[92:93], s[12:13], v223, s8, v[130:131]
	v_lshl_add_u64 v[92:93], v[92:93], 0, v[132:133]
	v_pk_mul_f32 v[94:95], v[98:99], v[168:169] op_sel_hi:[1,0]
	v_pk_mul_f32 v[96:97], v[96:97], v[168:169] op_sel_hi:[1,0]
	v_pk_mul_f32 v[98:99], v[90:91], v[168:169] op_sel_hi:[1,0]
	v_pk_mul_f32 v[90:91], v[88:89], v[168:169] op_sel_hi:[1,0]
	v_cvt_pk_bf16_f32 v88, v96, v97
	v_cvt_pk_bf16_f32 v89, v94, v95
	v_pk_mul_f32 v[86:87], v[86:87], v[168:169] op_sel_hi:[1,0]
	v_cvt_pk_bf16_f32 v90, v90, v91
	v_cvt_pk_bf16_f32 v91, v98, v99
	global_store_dwordx4 v[92:93], v[88:91], off
	v_pk_mul_f32 v[84:85], v[84:85], v[168:169] op_sel_hi:[1,0]
	s_nop 0
	v_pk_mul_f32 v[88:89], v[78:79], v[168:169] op_sel_hi:[1,0]
	v_pk_mul_f32 v[78:79], v[76:77], v[168:169] op_sel_hi:[1,0]
	v_cvt_pk_bf16_f32 v76, v84, v85
	v_cvt_pk_bf16_f32 v77, v86, v87
	s_nop 0
	v_cvt_pk_bf16_f32 v78, v78, v79
	v_cvt_pk_bf16_f32 v79, v88, v89
	global_store_dwordx4 v[92:93], v[76:79], off offset:256
	s_nop 1
	v_mad_i64_i32 v[76:77], s[12:13], v222, s8, v[130:131]
	v_lshl_add_u64 v[76:77], v[76:77], 0, v[132:133]
	v_pk_mul_f32 v[78:79], v[82:83], v[160:161] op_sel_hi:[1,0]
	v_pk_mul_f32 v[80:81], v[80:81], v[160:161] op_sel_hi:[1,0]
	v_pk_mul_f32 v[82:83], v[74:75], v[160:161] op_sel_hi:[1,0]
	v_pk_mul_f32 v[74:75], v[72:73], v[160:161] op_sel_hi:[1,0]
	v_cvt_pk_bf16_f32 v72, v80, v81
	v_cvt_pk_bf16_f32 v73, v78, v79
	v_pk_mul_f32 v[70:71], v[70:71], v[160:161] op_sel_hi:[1,0]
	v_cvt_pk_bf16_f32 v74, v74, v75
	v_cvt_pk_bf16_f32 v75, v82, v83
	global_store_dwordx4 v[76:77], v[72:75], off
	v_pk_mul_f32 v[68:69], v[68:69], v[160:161] op_sel_hi:[1,0]
	s_nop 0
	v_pk_mul_f32 v[72:73], v[66:67], v[160:161] op_sel_hi:[1,0]
	v_pk_mul_f32 v[66:67], v[64:65], v[160:161] op_sel_hi:[1,0]
	v_cvt_pk_bf16_f32 v64, v68, v69
	v_cvt_pk_bf16_f32 v65, v70, v71
	s_nop 0
	v_cvt_pk_bf16_f32 v66, v66, v67
	v_cvt_pk_bf16_f32 v67, v72, v73
	global_store_dwordx4 v[76:77], v[64:67], off offset:256
	s_nop 1
	v_mad_i64_i32 v[64:65], s[12:13], v221, s8, v[130:131]
	v_lshl_add_u64 v[64:65], v[64:65], 0, v[132:133]
	v_pk_mul_f32 v[62:63], v[62:63], v[152:153] op_sel_hi:[1,0]
	v_pk_mul_f32 v[60:61], v[60:61], v[152:153] op_sel_hi:[1,0]
	v_pk_mul_f32 v[66:67], v[58:59], v[152:153] op_sel_hi:[1,0]
	v_pk_mul_f32 v[58:59], v[56:57], v[152:153] op_sel_hi:[1,0]
	v_cvt_pk_bf16_f32 v56, v60, v61
	v_cvt_pk_bf16_f32 v57, v62, v63
	v_pk_mul_f32 v[54:55], v[54:55], v[152:153] op_sel_hi:[1,0]
	v_cvt_pk_bf16_f32 v58, v58, v59
	v_cvt_pk_bf16_f32 v59, v66, v67
	global_store_dwordx4 v[64:65], v[56:59], off
	v_pk_mul_f32 v[52:53], v[52:53], v[152:153] op_sel_hi:[1,0]
	s_nop 0
	v_pk_mul_f32 v[56:57], v[46:47], v[152:153] op_sel_hi:[1,0]
	v_pk_mul_f32 v[46:47], v[44:45], v[152:153] op_sel_hi:[1,0]
	v_cvt_pk_bf16_f32 v44, v52, v53
	v_cvt_pk_bf16_f32 v45, v54, v55
	s_nop 0
	v_cvt_pk_bf16_f32 v46, v46, v47
	v_cvt_pk_bf16_f32 v47, v56, v57
	global_store_dwordx4 v[64:65], v[44:47], off offset:256
	s_nop 1
	v_mad_i64_i32 v[44:45], s[12:13], v220, s8, v[130:131]
	v_lshl_add_u64 v[44:45], v[44:45], 0, v[132:133]
	v_pk_mul_f32 v[46:47], v[50:51], v[144:145] op_sel_hi:[1,0]
	v_pk_mul_f32 v[48:49], v[48:49], v[144:145] op_sel_hi:[1,0]
	v_pk_mul_f32 v[50:51], v[42:43], v[144:145] op_sel_hi:[1,0]
	v_pk_mul_f32 v[42:43], v[40:41], v[144:145] op_sel_hi:[1,0]
	v_cvt_pk_bf16_f32 v40, v48, v49
	v_cvt_pk_bf16_f32 v41, v46, v47
	v_pk_mul_f32 v[38:39], v[38:39], v[144:145] op_sel_hi:[1,0]
	v_cvt_pk_bf16_f32 v42, v42, v43
	v_cvt_pk_bf16_f32 v43, v50, v51
	global_store_dwordx4 v[44:45], v[40:43], off
	v_pk_mul_f32 v[36:37], v[36:37], v[144:145] op_sel_hi:[1,0]
	s_nop 0
	v_pk_mul_f32 v[40:41], v[30:31], v[144:145] op_sel_hi:[1,0]
	v_pk_mul_f32 v[30:31], v[28:29], v[144:145] op_sel_hi:[1,0]
	v_cvt_pk_bf16_f32 v28, v36, v37
	v_cvt_pk_bf16_f32 v29, v38, v39
	s_nop 0
	v_cvt_pk_bf16_f32 v30, v30, v31
	v_cvt_pk_bf16_f32 v31, v40, v41
	global_store_dwordx4 v[44:45], v[28:31], off offset:256
	s_nop 1
	v_mad_i64_i32 v[28:29], s[12:13], v219, s8, v[130:131]
	v_lshl_add_u64 v[28:29], v[28:29], 0, v[132:133]
	v_pk_mul_f32 v[30:31], v[34:35], v[136:137] op_sel_hi:[1,0]
	v_pk_mul_f32 v[32:33], v[32:33], v[136:137] op_sel_hi:[1,0]
	v_pk_mul_f32 v[34:35], v[26:27], v[136:137] op_sel_hi:[1,0]
	v_pk_mul_f32 v[26:27], v[24:25], v[136:137] op_sel_hi:[1,0]
	v_cvt_pk_bf16_f32 v24, v32, v33
	v_cvt_pk_bf16_f32 v25, v30, v31
	v_pk_mul_f32 v[22:23], v[22:23], v[136:137] op_sel_hi:[1,0]
	v_cvt_pk_bf16_f32 v26, v26, v27
	v_cvt_pk_bf16_f32 v27, v34, v35
	global_store_dwordx4 v[28:29], v[24:27], off
	v_pk_mul_f32 v[20:21], v[20:21], v[136:137] op_sel_hi:[1,0]
	s_nop 0
	v_pk_mul_f32 v[24:25], v[14:15], v[136:137] op_sel_hi:[1,0]
	v_pk_mul_f32 v[14:15], v[12:13], v[136:137] op_sel_hi:[1,0]
	v_cvt_pk_bf16_f32 v12, v20, v21
	v_cvt_pk_bf16_f32 v13, v22, v23
	s_nop 0
	v_cvt_pk_bf16_f32 v14, v14, v15
	v_cvt_pk_bf16_f32 v15, v24, v25
	global_store_dwordx4 v[28:29], v[12:15], off offset:256
	s_nop 1
	v_mad_i64_i32 v[12:13], s[12:13], v218, s8, v[130:131]
	v_lshl_add_u64 v[12:13], v[12:13], 0, v[132:133]
	v_pk_mul_f32 v[14:15], v[18:19], v[128:129] op_sel_hi:[1,0]
	v_pk_mul_f32 v[16:17], v[16:17], v[128:129] op_sel_hi:[1,0]
	v_pk_mul_f32 v[18:19], v[10:11], v[128:129] op_sel_hi:[1,0]
	v_pk_mul_f32 v[10:11], v[8:9], v[128:129] op_sel_hi:[1,0]
	v_cvt_pk_bf16_f32 v8, v16, v17
	v_cvt_pk_bf16_f32 v9, v14, v15
	s_movk_i32 s73, 0xc00
	v_cvt_pk_bf16_f32 v10, v10, v11
	v_cvt_pk_bf16_f32 v11, v18, v19
	global_store_dwordx4 v[12:13], v[8:11], off
	v_pk_mul_f32 v[6:7], v[6:7], v[128:129] op_sel_hi:[1,0]
	v_pk_mul_f32 v[4:5], v[4:5], v[128:129] op_sel_hi:[1,0]
	v_pk_mul_f32 v[8:9], v[2:3], v[128:129] op_sel_hi:[1,0]
	v_pk_mul_f32 v[2:3], v[0:1], v[128:129] op_sel_hi:[1,0]
	v_cvt_pk_bf16_f32 v0, v4, v5
	v_cvt_pk_bf16_f32 v1, v6, v7
	s_nop 0
	v_cvt_pk_bf16_f32 v2, v2, v3
	v_cvt_pk_bf16_f32 v3, v8, v9
	global_store_dwordx4 v[12:13], v[0:3], off offset:256
	s_and_b64 vcc, exec, s[40:41]
	s_mov_b64 s[12:13], -1
	s_cbranch_vccnz .LBB0_95
	s_andn2_b64 vcc, exec, s[6:7]
	s_cbranch_vccnz .LBB0_94
	s_barrier
	s_branch .LBB0_94
